# P10: the two wide score loads of the next sort group issued before the current group is sorted
# speedup vs baseline: 1.0247x; 1.0066x over previous
; DI void topk_half(const _Float16* __restrict__ sp, unsigned (&R)[16]) {
; #pragma unroll
;   for (int e = 0; e < 16; ++e) R[e] = 0u;
; #pragma unroll 1
;   for (int gi = 0; gi < 8; ++gi) {
;     unsigned Gk[16];
; #pragma unroll
;     for (int e = 0; e < 16; ++e) {
;       const int n = gi * 16 + e;
;       const unsigned bits = __builtin_bit_cast(unsigned short, sp[(long)n * NTOK]);
;       const unsigned o = (bits & 0x8000u) ? (~bits & 0xffffu) : (bits | 0x8000u);
;       Gk[e] = (o << 16) | (unsigned)(127 - n);
;     }
.LBB0_1183:
	v_alignbit_b32 v1, v129, v128, 15
	v_lshlrev_b32_e32 v4, 1, v1
	v_ashrrev_i32_e32 v5, 31, v4
	v_lshlrev_b64 v[4:5], 23, v[4:5]
	v_and_b32_e32 v1, 0x7fff, v26
	v_lshrrev_b64 v[2:3], 15, v[128:129]
	v_lshl_or_b32 v4, v1, 1, v4
	v_lshl_add_u64 v[6:7], s[40:41], 0, v[4:5]
	s_movk_i32 s91, 0x70
	v_mov_b32_e32 v35, 0
	v_mov_b32_e32 v24, 0
	v_mov_b32_e32 v40, 0
	v_mov_b32_e32 v41, 0
	v_mov_b32_e32 v39, 0
	v_mov_b32_e32 v25, 0
	v_mov_b32_e32 v38, 0
	v_mov_b32_e32 v36, 0
	v_mov_b32_e32 v33, 0
	v_mov_b32_e32 v32, 0
	v_mov_b32_e32 v31, 0
	v_mov_b32_e32 v30, 0
	v_mov_b32_e32 v3, 0
	v_mov_b32_e32 v1, 0
	v_mov_b32_e32 v34, 0
	v_mov_b32_e32 v37, 0
	v_lshrrev_b32_e32 v88, 3, v208
	v_and_b32_e32 v89, 7, v208
	v_lshlrev_b32_e32 v88, 16, v88
	v_lshl_add_u32 v88, v89, 4, v88
	v_lshlrev_b32_e32 v89, 1, v208
	v_sub_u32_e32 v88, v88, v89
	v_add_u32_e32 v86, v4, v88
	v_and_b32_e32 v100, 0x3c00, v209
	v_lshlrev_b32_e32 v100, 1, v100
	v_add_u32_e32 v101, v100, v89
	v_lshl_add_u32 v100, v208, 4, v100
	global_load_dwordx4 v[90:93], v86, s[40:41]
	v_add_u32_e32 v87, 0x80000, v86
	global_load_dwordx4 v[94:97], v87, s[40:41]
	v_add_u32_e32 v86, 0x100000, v86
.LBB0_1184:
	s_waitcnt vmcnt(0)
	ds_write_b128 v100, v[90:93]
	ds_write_b128 v100, v[94:97] offset:1024
	s_waitcnt lgkmcnt(0)
	global_load_dwordx4 v[90:93], v86, s[40:41]
	v_add_u32_e32 v87, 0x80000, v86
	global_load_dwordx4 v[94:97], v87, s[40:41]
	v_add_u32_e32 v86, 0x100000, v86
	ds_read_u16 v42, v101
	ds_read_u16 v47, v101 offset:128
	ds_read_u16 v46, v101 offset:256
	ds_read_u16 v45, v101 offset:384
	ds_read_u16 v44, v101 offset:512
	ds_read_u16 v43, v101 offset:640
	ds_read_u16 v17, v101 offset:768
	ds_read_u16 v16, v101 offset:896
	ds_read_u16 v14, v101 offset:1024
	ds_read_u16 v13, v101 offset:1152
	ds_read_u16 v12, v101 offset:1280
	ds_read_u16 v11, v101 offset:1408
	ds_read_u16 v10, v101 offset:1536
	ds_read_u16 v9, v101 offset:1664
	ds_read_u16 v8, v101 offset:1792
	ds_read_u16 v15, v101 offset:1920
	s_waitcnt lgkmcnt(0)
	v_and_b32_e32 v18, 0xffff, v42
	v_bitop3_b32 v19, v18, s57, v18 bitop3:0xc
	v_or_b32_e32 v18, 0x8000, v18
	v_cmp_gt_i16_e32 vcc, 0, v42
	v_and_b32_e32 v20, 0xffff, v47
	v_and_b32_e32 v21, 0xffff, v46
	v_and_b32_e32 v22, 0xffff, v45
	v_and_b32_e32 v23, 0xffff, v44
	v_and_b32_e32 v48, 0xffff, v43
	v_and_b32_e32 v49, 0xffff, v17
	v_and_b32_e32 v50, 0xffff, v16
	v_and_b32_e32 v51, 0xffff, v14
	v_and_b32_e32 v52, 0xffff, v13
	v_and_b32_e32 v53, 0xffff, v12
	v_and_b32_e32 v54, 0xffff, v11
	v_and_b32_e32 v55, 0xffff, v10
	v_and_b32_e32 v56, 0xffff, v9
	v_and_b32_e32 v57, 0xffff, v8
	v_and_b32_e32 v58, 0xffff, v15
	v_cndmask_b32_e32 v18, v18, v19, vcc
	v_bitop3_b32 v19, v20, s57, v20 bitop3:0xc
	v_or_b32_e32 v20, 0x8000, v20
	v_cmp_gt_i16_e32 vcc, 0, v47
	v_bitop3_b32 v42, v21, s57, v21 bitop3:0xc
	v_or_b32_e32 v21, 0x8000, v21
	v_cmp_gt_i16_e64 s[0:1], 0, v46
	v_bitop3_b32 v46, v22, s57, v22 bitop3:0xc
	v_or_b32_e32 v22, 0x8000, v22
	v_cmp_gt_i16_e64 s[6:7], 0, v45
	v_bitop3_b32 v45, v23, s57, v23 bitop3:0xc
	v_or_b32_e32 v23, 0x8000, v23
	v_cmp_gt_i16_e64 s[8:9], 0, v44
	v_bitop3_b32 v44, v48, s57, v48 bitop3:0xc
	v_or_b32_e32 v47, 0x8000, v48
	v_cmp_gt_i16_e64 s[10:11], 0, v43
	v_bitop3_b32 v43, v49, s57, v49 bitop3:0xc
	v_or_b32_e32 v48, 0x8000, v49
	v_cmp_gt_i16_e64 s[12:13], 0, v17
	v_bitop3_b32 v17, v50, s57, v50 bitop3:0xc
	v_or_b32_e32 v49, 0x8000, v50
	v_cmp_gt_i16_e64 s[14:15], 0, v16
	v_bitop3_b32 v16, v51, s57, v51 bitop3:0xc
	v_or_b32_e32 v50, 0x8000, v51
	v_cmp_gt_i16_e64 s[16:17], 0, v14
	v_bitop3_b32 v14, v52, s57, v52 bitop3:0xc
	v_or_b32_e32 v51, 0x8000, v52
	v_cmp_gt_i16_e64 s[18:19], 0, v13
	v_bitop3_b32 v13, v53, s57, v53 bitop3:0xc
	v_or_b32_e32 v52, 0x8000, v53
	v_cmp_gt_i16_e64 s[20:21], 0, v12
	v_bitop3_b32 v12, v54, s57, v54 bitop3:0xc
	v_or_b32_e32 v53, 0x8000, v54
	v_cmp_gt_i16_e64 s[24:25], 0, v11
	v_bitop3_b32 v11, v55, s57, v55 bitop3:0xc
	v_or_b32_e32 v54, 0x8000, v55
	v_cmp_gt_i16_e64 s[26:27], 0, v10
	v_bitop3_b32 v10, v56, s57, v56 bitop3:0xc
	v_or_b32_e32 v55, 0x8000, v56
	v_cmp_gt_i16_e64 s[28:29], 0, v9
	v_bitop3_b32 v9, v57, s57, v57 bitop3:0xc
	v_or_b32_e32 v56, 0x8000, v57
	v_cmp_gt_i16_e64 s[30:31], 0, v8
	v_bitop3_b32 v8, v58, s57, v58 bitop3:0xc
	v_or_b32_e32 v57, 0x8000, v58
	v_cmp_gt_i16_e64 s[34:35], 0, v15
	v_lshlrev_b32_e32 v15, 16, v18
	v_cndmask_b32_e32 v18, v20, v19, vcc
	v_cndmask_b32_e64 v19, v21, v42, s[0:1]
	v_cndmask_b32_e64 v20, v22, v46, s[6:7]
	v_cndmask_b32_e64 v21, v23, v45, s[8:9]
	v_cndmask_b32_e64 v22, v47, v44, s[10:11]
	v_cndmask_b32_e64 v23, v48, v43, s[12:13]
	v_cndmask_b32_e64 v17, v49, v17, s[14:15]
	v_cndmask_b32_e64 v16, v50, v16, s[16:17]
	v_cndmask_b32_e64 v14, v51, v14, s[18:19]
	v_cndmask_b32_e64 v13, v52, v13, s[20:21]
	v_cndmask_b32_e64 v12, v53, v12, s[24:25]
	v_cndmask_b32_e64 v11, v54, v11, s[26:27]
	v_cndmask_b32_e64 v10, v55, v10, s[28:29]
	v_cndmask_b32_e64 v9, v56, v9, s[30:31]
	v_cndmask_b32_e64 v8, v57, v8, s[34:35]
	v_lshlrev_b32_e32 v18, 16, v18
	v_lshlrev_b32_e32 v19, 16, v19
	v_lshlrev_b32_e32 v20, 16, v20
	v_lshlrev_b32_e32 v21, 16, v21
	v_lshlrev_b32_e32 v22, 16, v22
	v_lshlrev_b32_e32 v23, 16, v23
	v_lshlrev_b32_e32 v17, 16, v17
	v_lshlrev_b32_e32 v16, 16, v16
	v_lshlrev_b32_e32 v14, 16, v14
	v_lshlrev_b32_e32 v13, 16, v13
	v_lshlrev_b32_e32 v12, 16, v12
	v_lshlrev_b32_e32 v11, 16, v11
	v_lshlrev_b32_e32 v10, 16, v10
	v_lshlrev_b32_e32 v9, 16, v9
	v_add3_u32 v15, s91, v15, 15
	v_lshl_add_u32 v8, v8, 16, s91
	v_add3_u32 v18, s91, v18, 14
	v_add3_u32 v19, s91, v19, 13
	v_add3_u32 v20, s91, v20, 12
	v_add3_u32 v21, s91, v21, 11
	v_add3_u32 v22, s91, v22, 10
	v_add3_u32 v23, s91, v23, 9
; DI void topk_half(const _Float16* __restrict__ sp, unsigned (&R)[16]) {
; #pragma unroll
;   for (int e = 0; e < 16; ++e) R[e] = 0u;
; #pragma unroll 1
;   for (int gi = 0; gi < 8; ++gi) {
;     unsigned Gk[16];
; #pragma unroll
;     for (int e = 0; e < 16; ++e) {
;       const int n = gi * 16 + e;
;       const unsigned bits = __builtin_bit_cast(unsigned short, sp[(long)n * NTOK]);
;       const unsigned o = (bits & 0x8000u) ? (~bits & 0xffffu) : (bits | 0x8000u);
;       Gk[e] = (o << 16) | (unsigned)(127 - n);
;     }
;     SORT16(Gk)
;     MERGE16(R, Gk)
;   }
	v_add3_u32 v17, s91, v17, 8
	v_add3_u32 v16, s91, v16, 7
	v_add3_u32 v14, s91, v14, 6
	v_add3_u32 v13, s91, v13, 5
	v_add3_u32 v12, s91, v12, 4
	v_add3_u32 v11, s91, v11, 3
	v_add3_u32 v10, s91, v10, 2
	v_add3_u32 v9, s91, v9, 1
	v_max_u32_e32 v42, v15, v18
	v_min_u32_e32 v15, v15, v18
	v_max_u32_e32 v18, v19, v20
	v_min_u32_e32 v19, v19, v20
	v_max_u32_e32 v20, v21, v22
	v_min_u32_e32 v21, v21, v22
	v_max_u32_e32 v22, v23, v17
	v_min_u32_e32 v17, v23, v17
	v_max_u32_e32 v23, v16, v14
	v_min_u32_e32 v14, v16, v14
	v_max_u32_e32 v16, v13, v12
	v_min_u32_e32 v12, v13, v12
	v_max_u32_e32 v13, v11, v10
	v_min_u32_e32 v10, v11, v10
	v_max_u32_e32 v11, v9, v8
	v_min_u32_e32 v8, v9, v8
	v_max_u32_e32 v9, v42, v18
	v_min_u32_e32 v18, v42, v18
	v_max_u32_e32 v42, v15, v19
	v_min_u32_e32 v15, v15, v19
	v_max_u32_e32 v19, v20, v22
	v_min_u32_e32 v20, v20, v22
	v_max_u32_e32 v22, v21, v17
	v_min_u32_e32 v17, v21, v17
	v_max_u32_e32 v21, v23, v16
	v_min_u32_e32 v16, v23, v16
	v_max_u32_e32 v23, v14, v12
	v_min_u32_e32 v12, v14, v12
	v_max_u32_e32 v14, v13, v11
	v_min_u32_e32 v11, v13, v11
	v_max_u32_e32 v13, v10, v8
	v_min_u32_e32 v8, v10, v8
	v_max_u32_e32 v10, v42, v18
	v_min_u32_e32 v18, v42, v18
	v_max_u32_e32 v42, v22, v20
	v_min_u32_e32 v20, v22, v20
	v_max_u32_e32 v22, v23, v16
	v_min_u32_e32 v16, v23, v16
	v_max_u32_e32 v23, v13, v11
	v_min_u32_e32 v11, v13, v11
	v_max_u32_e32 v13, v9, v19
	v_min_u32_e32 v9, v9, v19
	v_max_u32_e32 v19, v15, v17
	v_min_u32_e32 v15, v15, v17
	v_max_u32_e32 v17, v21, v14
	v_min_u32_e32 v14, v21, v14
	v_max_u32_e32 v21, v12, v8
	v_min_u32_e32 v8, v12, v8
	v_max_u32_e32 v12, v10, v42
	v_min_u32_e32 v10, v10, v42
	v_max_u32_e32 v42, v18, v20
	v_min_u32_e32 v18, v18, v20
	v_max_u32_e32 v20, v22, v23
	v_min_u32_e32 v22, v22, v23
	v_max_u32_e32 v23, v16, v11
	v_min_u32_e32 v11, v16, v11
	v_min_u32_e32 v16, v13, v17
	v_max_u32_e32 v43, v15, v8
	v_min_u32_e32 v8, v15, v8
	v_max3_u32 v13, v37, v13, v17
	v_max_u32_e32 v15, v42, v9
	v_min_u32_e32 v9, v42, v9
	v_max_u32_e32 v17, v19, v10
	v_min_u32_e32 v10, v19, v10
	v_max_u32_e32 v19, v23, v14
	v_min_u32_e32 v14, v23, v14
	v_max_u32_e32 v23, v21, v22
	v_min_u32_e32 v21, v21, v22
	v_max_u32_e32 v22, v12, v15
	v_min_u32_e32 v12, v12, v15
	v_max_u32_e32 v15, v17, v9
	v_min_u32_e32 v9, v17, v9
	v_max_u32_e32 v17, v10, v18
	v_min_u32_e32 v10, v10, v18
	v_max_u32_e32 v18, v20, v19
	v_min_u32_e32 v19, v20, v19
	v_max_u32_e32 v20, v23, v14
	v_min_u32_e32 v14, v23, v14
	v_max_u32_e32 v23, v21, v11
	v_min_u32_e32 v11, v21, v11
	v_max_u32_e32 v21, v22, v18
	v_min_u32_e32 v18, v22, v18
	v_max_u32_e32 v22, v12, v19
	v_min_u32_e32 v12, v12, v19
	v_max_u32_e32 v19, v15, v20
	v_min_u32_e32 v15, v15, v20
	v_max_u32_e32 v20, v9, v14
	v_min_u32_e32 v9, v9, v14
	v_max_u32_e32 v14, v17, v23
	v_min_u32_e32 v17, v17, v23
	v_max_u32_e32 v23, v10, v11
	v_min_u32_e32 v10, v10, v11
	v_max_u32_e32 v11, v20, v16
	v_min_u32_e32 v16, v20, v16
	v_max_u32_e32 v20, v14, v18
	v_min_u32_e32 v14, v14, v18
	v_max_u32_e32 v18, v23, v12
	v_min_u32_e32 v12, v23, v12
	v_max_u32_e32 v23, v43, v15
	v_min_u32_e32 v15, v43, v15
	v_max_u32_e32 v8, v35, v8
	v_max_u32_e32 v35, v22, v11
	v_min_u32_e32 v11, v22, v11
	v_max_u32_e32 v22, v19, v20
	v_min_u32_e32 v19, v19, v20
	v_max_u32_e32 v20, v18, v16
	v_min_u32_e32 v16, v18, v16
	v_max_u32_e32 v18, v23, v14
	v_min_u32_e32 v14, v23, v14
	v_max_u32_e32 v23, v12, v9
	v_min_u32_e32 v9, v12, v9
	v_max_u32_e32 v12, v15, v17
	v_min_u32_e32 v15, v15, v17
	v_min_u32_e32 v17, v21, v35
	v_min_u32_e32 v37, v22, v11
	v_min_u32_e32 v42, v19, v20
	v_min_u32_e32 v43, v18, v16
	v_min_u32_e32 v44, v14, v23
	v_min_u32_e32 v45, v12, v9
	v_min_u32_e32 v46, v15, v10
	v_max3_u32 v10, v40, v15, v10
	v_max3_u32 v9, v39, v12, v9
	v_max3_u32 v12, v38, v14, v23
	v_max3_u32 v14, v33, v18, v16
	v_max3_u32 v15, v31, v19, v20
	v_max3_u32 v3, v3, v22, v11
	v_max3_u32 v11, v34, v21, v35
	v_max_u32_e32 v16, v24, v46
	v_max_u32_e32 v18, v41, v45
	v_max_u32_e32 v19, v25, v44
	v_max_u32_e32 v20, v36, v43
	v_max_u32_e32 v21, v32, v42
	v_max_u32_e32 v22, v30, v37
	v_max_u32_e32 v1, v1, v17
	v_max_u32_e32 v17, v8, v14
	v_min_u32_e32 v8, v8, v14
	v_max_u32_e32 v14, v10, v15
	v_min_u32_e32 v10, v10, v15
	v_max_u32_e32 v15, v9, v3
	v_min_u32_e32 v3, v9, v3
	v_max_u32_e32 v9, v12, v11
	v_min_u32_e32 v11, v12, v11
	v_max_u32_e32 v12, v16, v21
	v_min_u32_e32 v16, v16, v21
	v_max_u32_e32 v21, v18, v22
	v_min_u32_e32 v18, v18, v22
	v_max_u32_e32 v22, v19, v1
	v_min_u32_e32 v1, v19, v1
	v_max_u32_e32 v19, v20, v13
	v_min_u32_e32 v13, v20, v13
	v_max_u32_e32 v20, v17, v15
	v_min_u32_e32 v15, v17, v15
	v_max_u32_e32 v17, v14, v9
	v_min_u32_e32 v9, v14, v9
	v_max_u32_e32 v14, v8, v3
	v_min_u32_e32 v3, v8, v3
	v_max_u32_e32 v8, v10, v11
	v_min_u32_e32 v10, v10, v11
	v_max_u32_e32 v11, v12, v22
	v_min_u32_e32 v12, v12, v22
	v_max_u32_e32 v22, v21, v19
	v_min_u32_e32 v19, v21, v19
	v_max_u32_e32 v21, v16, v1
	v_min_u32_e32 v1, v16, v1
	v_max_u32_e32 v16, v18, v13
	v_min_u32_e32 v13, v18, v13
	s_add_i32 s91, s91, -16
	v_max_u32_e32 v18, v20, v17
	v_min_u32_e32 v17, v20, v17
	v_max_u32_e32 v20, v15, v9
	v_min_u32_e32 v9, v15, v9
	v_max_u32_e32 v15, v14, v8
	v_min_u32_e32 v8, v14, v8
	v_max_u32_e32 v14, v3, v10
	v_min_u32_e32 v10, v3, v10
	v_max_u32_e32 v3, v11, v22
	v_min_u32_e32 v11, v11, v22
	v_max_u32_e32 v22, v12, v19
	v_min_u32_e32 v12, v12, v19
	v_max_u32_e32 v19, v21, v16
	v_min_u32_e32 v16, v21, v16
	v_max_u32_e32 v21, v1, v13
	v_min_u32_e32 v13, v1, v13
	s_cmp_lg_u32 s91, -16
	v_max_u32_e32 v35, v18, v3
	v_min_u32_e32 v24, v18, v3
	v_max_u32_e32 v40, v17, v11
	v_min_u32_e32 v41, v17, v11
	v_max_u32_e32 v39, v20, v22
	v_min_u32_e32 v25, v20, v22
	v_max_u32_e32 v38, v9, v12
	v_min_u32_e32 v36, v9, v12
	v_max_u32_e32 v33, v15, v19
	v_min_u32_e32 v32, v15, v19
	v_max_u32_e32 v31, v8, v16
	v_min_u32_e32 v30, v8, v16
	v_max_u32_e32 v3, v14, v21
	v_min_u32_e32 v1, v14, v21
	v_max_u32_e32 v34, v10, v13
	v_min_u32_e32 v37, v10, v13
	s_cbranch_scc1 .LBB0_1184
	v_lshl_add_u64 v[4:5], s[46:47], 0, v[4:5]
	v_mov_b32_e32 v55, 0
	s_movk_i32 s91, 0x70
	v_mov_b32_e32 v49, 0
	v_mov_b32_e32 v54, 0
	v_mov_b32_e32 v46, 0
	v_mov_b32_e32 v52, 0
	v_mov_b32_e32 v45, 0
	v_mov_b32_e32 v53, 0
	v_mov_b32_e32 v44, 0
	v_mov_b32_e32 v50, 0
	v_mov_b32_e32 v43, 0
	v_mov_b32_e32 v51, 0
	v_mov_b32_e32 v42, 0
	v_mov_b32_e32 v47, 0
	v_mov_b32_e32 v23, 0
	v_mov_b32_e32 v48, 0
	v_mov_b32_e32 v56, 0
; DI void topk_half(const _Float16* __restrict__ sp, unsigned (&R)[16]) {
;     ...
;   for (int gi = 0; gi < 8; ++gi) {
;     unsigned Gk[16];
; #pragma unroll
;     for (int e = 0; e < 16; ++e) {
;       const int n = gi * 16 + e;
;       const unsigned bits = __builtin_bit_cast(unsigned short, sp[(long)n * NTOK]);
;       const unsigned o = (bits & 0x8000u) ? (~bits & 0xffffu) : (bits | 0x8000u);
;       Gk[e] = (o << 16) | (unsigned)(127 - n);
;     }
.LBB0_1186:
	s_waitcnt vmcnt(0)
	ds_write_b128 v100, v[90:93]
	ds_write_b128 v100, v[94:97] offset:1024
	s_waitcnt lgkmcnt(0)
	global_load_dwordx4 v[90:93], v86, s[40:41]
	v_add_u32_e32 v87, 0x80000, v86
	global_load_dwordx4 v[94:97], v87, s[40:41]
	v_add_u32_e32 v86, 0x100000, v86
	ds_read_u16 v22, v101
	ds_read_u16 v61, v101 offset:128
	ds_read_u16 v60, v101 offset:256
	ds_read_u16 v59, v101 offset:384
	ds_read_u16 v58, v101 offset:512
	ds_read_u16 v57, v101 offset:640
	ds_read_u16 v15, v101 offset:768
	ds_read_u16 v14, v101 offset:896
	ds_read_u16 v12, v101 offset:1024
	ds_read_u16 v11, v101 offset:1152
	ds_read_u16 v10, v101 offset:1280
	ds_read_u16 v9, v101 offset:1408
	ds_read_u16 v8, v101 offset:1536
	ds_read_u16 v7, v101 offset:1664
	ds_read_u16 v6, v101 offset:1792
	ds_read_u16 v13, v101 offset:1920
	s_waitcnt lgkmcnt(0)
	v_and_b32_e32 v16, 0xffff, v22
	v_bitop3_b32 v17, v16, s57, v16 bitop3:0xc
	v_or_b32_e32 v16, 0x8000, v16
	v_cmp_gt_i16_e32 vcc, 0, v22
	v_and_b32_e32 v18, 0xffff, v61
	v_and_b32_e32 v19, 0xffff, v60
	v_and_b32_e32 v20, 0xffff, v59
	v_and_b32_e32 v21, 0xffff, v58
	v_and_b32_e32 v62, 0xffff, v57
	v_and_b32_e32 v63, 0xffff, v15
	v_and_b32_e32 v64, 0xffff, v14
	v_and_b32_e32 v65, 0xffff, v12
	v_and_b32_e32 v66, 0xffff, v11
	v_and_b32_e32 v67, 0xffff, v10
	v_and_b32_e32 v68, 0xffff, v9
	v_and_b32_e32 v69, 0xffff, v8
	v_and_b32_e32 v70, 0xffff, v7
	v_and_b32_e32 v71, 0xffff, v6
	v_and_b32_e32 v72, 0xffff, v13
	v_cndmask_b32_e32 v16, v16, v17, vcc
	v_bitop3_b32 v17, v18, s57, v18 bitop3:0xc
	v_or_b32_e32 v18, 0x8000, v18
	v_cmp_gt_i16_e32 vcc, 0, v61
	v_bitop3_b32 v22, v19, s57, v19 bitop3:0xc
	v_or_b32_e32 v19, 0x8000, v19
	v_cmp_gt_i16_e64 s[0:1], 0, v60
	v_bitop3_b32 v60, v20, s57, v20 bitop3:0xc
	v_or_b32_e32 v20, 0x8000, v20
	v_cmp_gt_i16_e64 s[6:7], 0, v59
	v_bitop3_b32 v59, v21, s57, v21 bitop3:0xc
	v_or_b32_e32 v21, 0x8000, v21
	v_cmp_gt_i16_e64 s[8:9], 0, v58
	v_bitop3_b32 v58, v62, s57, v62 bitop3:0xc
	v_or_b32_e32 v61, 0x8000, v62
	v_cmp_gt_i16_e64 s[10:11], 0, v57
	v_bitop3_b32 v57, v63, s57, v63 bitop3:0xc
	v_or_b32_e32 v62, 0x8000, v63
	v_cmp_gt_i16_e64 s[12:13], 0, v15
	v_bitop3_b32 v15, v64, s57, v64 bitop3:0xc
	v_or_b32_e32 v63, 0x8000, v64
	v_cmp_gt_i16_e64 s[14:15], 0, v14
	v_bitop3_b32 v14, v65, s57, v65 bitop3:0xc
	v_or_b32_e32 v64, 0x8000, v65
	v_cmp_gt_i16_e64 s[16:17], 0, v12
	v_bitop3_b32 v12, v66, s57, v66 bitop3:0xc
	v_or_b32_e32 v65, 0x8000, v66
	v_cmp_gt_i16_e64 s[18:19], 0, v11
	v_bitop3_b32 v11, v67, s57, v67 bitop3:0xc
	v_or_b32_e32 v66, 0x8000, v67
	v_cmp_gt_i16_e64 s[20:21], 0, v10
	v_bitop3_b32 v10, v68, s57, v68 bitop3:0xc
	v_or_b32_e32 v67, 0x8000, v68
	v_cmp_gt_i16_e64 s[24:25], 0, v9
	v_bitop3_b32 v9, v69, s57, v69 bitop3:0xc
	v_or_b32_e32 v68, 0x8000, v69
	v_cmp_gt_i16_e64 s[26:27], 0, v8
	v_bitop3_b32 v8, v70, s57, v70 bitop3:0xc
	v_or_b32_e32 v69, 0x8000, v70
	v_cmp_gt_i16_e64 s[28:29], 0, v7
	v_bitop3_b32 v7, v71, s57, v71 bitop3:0xc
	v_or_b32_e32 v70, 0x8000, v71
	v_cmp_gt_i16_e64 s[30:31], 0, v6
	v_bitop3_b32 v6, v72, s57, v72 bitop3:0xc
	v_or_b32_e32 v71, 0x8000, v72
	v_cmp_gt_i16_e64 s[34:35], 0, v13
	v_lshlrev_b32_e32 v13, 16, v16
	v_cndmask_b32_e32 v16, v18, v17, vcc
	v_cndmask_b32_e64 v17, v19, v22, s[0:1]
	v_cndmask_b32_e64 v18, v20, v60, s[6:7]
	v_cndmask_b32_e64 v19, v21, v59, s[8:9]
	v_cndmask_b32_e64 v20, v61, v58, s[10:11]
	v_cndmask_b32_e64 v21, v62, v57, s[12:13]
	v_cndmask_b32_e64 v15, v63, v15, s[14:15]
	v_cndmask_b32_e64 v14, v64, v14, s[16:17]
	v_cndmask_b32_e64 v12, v65, v12, s[18:19]
	v_cndmask_b32_e64 v11, v66, v11, s[20:21]
	v_cndmask_b32_e64 v10, v67, v10, s[24:25]
	v_cndmask_b32_e64 v9, v68, v9, s[26:27]
	v_cndmask_b32_e64 v8, v69, v8, s[28:29]
	v_cndmask_b32_e64 v7, v70, v7, s[30:31]
	v_cndmask_b32_e64 v6, v71, v6, s[34:35]
	v_lshlrev_b32_e32 v16, 16, v16
	v_lshlrev_b32_e32 v17, 16, v17
	v_lshlrev_b32_e32 v18, 16, v18
	v_lshlrev_b32_e32 v19, 16, v19
	v_lshlrev_b32_e32 v20, 16, v20
	v_lshlrev_b32_e32 v21, 16, v21
	v_lshlrev_b32_e32 v15, 16, v15
	v_lshlrev_b32_e32 v14, 16, v14
	v_lshlrev_b32_e32 v12, 16, v12
	v_lshlrev_b32_e32 v11, 16, v11
	v_lshlrev_b32_e32 v10, 16, v10
	v_lshlrev_b32_e32 v9, 16, v9
	v_lshlrev_b32_e32 v8, 16, v8
	v_lshlrev_b32_e32 v7, 16, v7
	v_add3_u32 v13, s91, v13, 15
	v_lshl_add_u32 v6, v6, 16, s91
	v_add3_u32 v16, s91, v16, 14
	v_add3_u32 v17, s91, v17, 13
	v_add3_u32 v18, s91, v18, 12
	v_add3_u32 v19, s91, v19, 11
	v_add3_u32 v20, s91, v20, 10
	v_add3_u32 v21, s91, v21, 9
	v_add3_u32 v15, s91, v15, 8
	v_add3_u32 v14, s91, v14, 7
	v_add3_u32 v12, s91, v12, 6
	v_add3_u32 v11, s91, v11, 5
	v_add3_u32 v10, s91, v10, 4
	v_add3_u32 v9, s91, v9, 3
	v_add3_u32 v8, s91, v8, 2
	v_add3_u32 v7, s91, v7, 1
	v_max_u32_e32 v22, v13, v16
	v_min_u32_e32 v13, v13, v16
	v_max_u32_e32 v16, v17, v18
	v_min_u32_e32 v17, v17, v18
	v_max_u32_e32 v18, v19, v20
	v_min_u32_e32 v19, v19, v20
	v_max_u32_e32 v20, v21, v15
	v_min_u32_e32 v15, v21, v15
	v_max_u32_e32 v21, v14, v12
	v_min_u32_e32 v12, v14, v12
	v_max_u32_e32 v14, v11, v10
	v_min_u32_e32 v10, v11, v10
	v_max_u32_e32 v11, v9, v8
	v_min_u32_e32 v8, v9, v8
	v_max_u32_e32 v9, v7, v6
	v_min_u32_e32 v6, v7, v6
	v_max_u32_e32 v7, v22, v16
	v_min_u32_e32 v16, v22, v16
	v_max_u32_e32 v22, v13, v17
	v_min_u32_e32 v13, v13, v17
	v_max_u32_e32 v17, v18, v20
	v_min_u32_e32 v18, v18, v20
	v_max_u32_e32 v20, v19, v15
	v_min_u32_e32 v15, v19, v15
	v_max_u32_e32 v19, v21, v14
	v_min_u32_e32 v14, v21, v14
	v_max_u32_e32 v21, v12, v10
	v_min_u32_e32 v10, v12, v10
	v_max_u32_e32 v12, v11, v9
	v_min_u32_e32 v9, v11, v9
	v_max_u32_e32 v11, v8, v6
	v_min_u32_e32 v6, v8, v6
	v_max_u32_e32 v8, v22, v16
; DI void topk_half(const _Float16* __restrict__ sp, unsigned (&R)[16]) {
; #pragma unroll
;   for (int e = 0; e < 16; ++e) R[e] = 0u;
; #pragma unroll 1
;   for (int gi = 0; gi < 8; ++gi) {
;     unsigned Gk[16];
; #pragma unroll
;     for (int e = 0; e < 16; ++e) {
;       const int n = gi * 16 + e;
;       const unsigned bits = __builtin_bit_cast(unsigned short, sp[(long)n * NTOK]);
;       const unsigned o = (bits & 0x8000u) ? (~bits & 0xffffu) : (bits | 0x8000u);
;       Gk[e] = (o << 16) | (unsigned)(127 - n);
;     }
;     SORT16(Gk)
;     MERGE16(R, Gk)
;   }
	v_min_u32_e32 v16, v22, v16
	v_max_u32_e32 v22, v20, v18
	v_min_u32_e32 v18, v20, v18
	v_max_u32_e32 v20, v21, v14
	v_min_u32_e32 v14, v21, v14
	v_max_u32_e32 v21, v11, v9
	v_min_u32_e32 v9, v11, v9
	v_max_u32_e32 v11, v7, v17
	v_min_u32_e32 v7, v7, v17
	v_max_u32_e32 v17, v13, v15
	v_min_u32_e32 v13, v13, v15
	v_max_u32_e32 v15, v19, v12
	v_min_u32_e32 v12, v19, v12
	v_max_u32_e32 v19, v10, v6
	v_min_u32_e32 v6, v10, v6
	v_max_u32_e32 v10, v8, v22
	v_min_u32_e32 v8, v8, v22
	v_max_u32_e32 v22, v16, v18
	v_min_u32_e32 v16, v16, v18
	v_max_u32_e32 v18, v20, v21
	v_min_u32_e32 v20, v20, v21
	v_max_u32_e32 v21, v14, v9
	v_min_u32_e32 v9, v14, v9
	v_min_u32_e32 v14, v11, v15
	v_max_u32_e32 v57, v13, v6
	v_min_u32_e32 v6, v13, v6
	v_max3_u32 v11, v56, v11, v15
	v_max_u32_e32 v13, v22, v7
	v_min_u32_e32 v7, v22, v7
	v_max_u32_e32 v15, v17, v8
	v_min_u32_e32 v8, v17, v8
	v_max_u32_e32 v17, v21, v12
	v_min_u32_e32 v12, v21, v12
	v_max_u32_e32 v21, v19, v20
	v_min_u32_e32 v19, v19, v20
	v_max_u32_e32 v20, v10, v13
	v_min_u32_e32 v10, v10, v13
	v_max_u32_e32 v13, v15, v7
	v_min_u32_e32 v7, v15, v7
	v_max_u32_e32 v15, v8, v16
	v_min_u32_e32 v8, v8, v16
	v_max_u32_e32 v16, v18, v17
	v_min_u32_e32 v17, v18, v17
	v_max_u32_e32 v18, v21, v12
	v_min_u32_e32 v12, v21, v12
	v_max_u32_e32 v21, v19, v9
	v_min_u32_e32 v9, v19, v9
	v_max_u32_e32 v19, v20, v16
	v_min_u32_e32 v16, v20, v16
	v_max_u32_e32 v20, v10, v17
	v_min_u32_e32 v10, v10, v17
	v_max_u32_e32 v17, v13, v18
	v_min_u32_e32 v13, v13, v18
	v_max_u32_e32 v18, v7, v12
	v_min_u32_e32 v7, v7, v12
	v_max_u32_e32 v12, v15, v21
	v_min_u32_e32 v15, v15, v21
	v_max_u32_e32 v21, v8, v9
	v_min_u32_e32 v8, v8, v9
	v_max_u32_e32 v9, v18, v14
	v_min_u32_e32 v14, v18, v14
	v_max_u32_e32 v18, v12, v16
	v_min_u32_e32 v12, v12, v16
	v_max_u32_e32 v16, v21, v10
	v_min_u32_e32 v10, v21, v10
	v_max_u32_e32 v21, v57, v13
	v_min_u32_e32 v13, v57, v13
	v_max_u32_e32 v22, v20, v9
	v_min_u32_e32 v9, v20, v9
	v_max_u32_e32 v20, v17, v18
	v_min_u32_e32 v17, v17, v18
	v_max_u32_e32 v18, v16, v14
	v_min_u32_e32 v14, v16, v14
	v_max_u32_e32 v16, v21, v12
	v_min_u32_e32 v12, v21, v12
	v_max_u32_e32 v21, v10, v7
	v_min_u32_e32 v7, v10, v7
	v_max_u32_e32 v10, v13, v15
	v_min_u32_e32 v13, v13, v15
	v_max_u32_e32 v6, v55, v6
	v_min_u32_e32 v15, v19, v22
	v_min_u32_e32 v55, v20, v9
	v_min_u32_e32 v56, v17, v18
	v_min_u32_e32 v57, v16, v14
	v_min_u32_e32 v58, v12, v21
	v_min_u32_e32 v59, v10, v7
	v_min_u32_e32 v60, v13, v8
	v_max3_u32 v8, v54, v13, v8
	v_max3_u32 v7, v52, v10, v7
	v_max3_u32 v10, v53, v12, v21
	v_max3_u32 v12, v50, v16, v14
	v_max3_u32 v13, v51, v17, v18
	v_max3_u32 v9, v47, v20, v9
	v_max3_u32 v14, v48, v19, v22
	v_max_u32_e32 v16, v49, v60
	v_max_u32_e32 v17, v46, v59
	v_max_u32_e32 v18, v45, v58
	v_max_u32_e32 v19, v44, v57
	v_max_u32_e32 v20, v43, v56
	v_max_u32_e32 v21, v42, v55
	v_max_u32_e32 v15, v23, v15
	v_max_u32_e32 v22, v6, v12
	v_min_u32_e32 v6, v6, v12
	v_max_u32_e32 v12, v8, v13
	v_min_u32_e32 v8, v8, v13
	v_max_u32_e32 v13, v7, v9
	v_min_u32_e32 v7, v7, v9
	v_max_u32_e32 v9, v10, v14
	v_min_u32_e32 v10, v10, v14
	v_max_u32_e32 v14, v16, v20
	v_min_u32_e32 v16, v16, v20
	v_max_u32_e32 v20, v17, v21
	v_min_u32_e32 v17, v17, v21
	v_max_u32_e32 v21, v18, v15
	v_min_u32_e32 v15, v18, v15
	v_max_u32_e32 v18, v19, v11
	v_min_u32_e32 v11, v19, v11
	v_max_u32_e32 v19, v22, v13
	v_min_u32_e32 v13, v22, v13
	v_max_u32_e32 v22, v12, v9
	v_min_u32_e32 v9, v12, v9
	v_max_u32_e32 v12, v6, v7
	v_min_u32_e32 v6, v6, v7
	v_max_u32_e32 v7, v8, v10
	v_min_u32_e32 v8, v8, v10
	v_max_u32_e32 v10, v14, v21
	v_min_u32_e32 v14, v14, v21
	v_max_u32_e32 v21, v20, v18
	v_min_u32_e32 v18, v20, v18
	v_max_u32_e32 v20, v16, v15
	v_min_u32_e32 v15, v16, v15
	v_max_u32_e32 v16, v17, v11
	v_min_u32_e32 v11, v17, v11
	s_add_i32 s91, s91, -16
	v_max_u32_e32 v17, v19, v22
	v_min_u32_e32 v19, v19, v22
	v_max_u32_e32 v22, v13, v9
	v_min_u32_e32 v9, v13, v9
	v_max_u32_e32 v13, v12, v7
	v_min_u32_e32 v7, v12, v7
	v_max_u32_e32 v12, v6, v8
	v_min_u32_e32 v6, v6, v8
	v_max_u32_e32 v8, v10, v21
	v_min_u32_e32 v10, v10, v21
	v_max_u32_e32 v21, v14, v18
	v_min_u32_e32 v14, v14, v18
	v_max_u32_e32 v18, v20, v16
	v_min_u32_e32 v16, v20, v16
	v_max_u32_e32 v20, v15, v11
	v_min_u32_e32 v11, v15, v11
	s_cmp_lg_u32 s91, -16
	v_max_u32_e32 v55, v17, v8
	v_min_u32_e32 v49, v17, v8
	v_max_u32_e32 v54, v19, v10
	v_min_u32_e32 v46, v19, v10
	v_max_u32_e32 v52, v22, v21
	v_min_u32_e32 v45, v22, v21
	v_max_u32_e32 v53, v9, v14
	v_min_u32_e32 v44, v9, v14
	v_max_u32_e32 v50, v13, v18
	v_min_u32_e32 v43, v13, v18
	v_max_u32_e32 v51, v7, v16
	v_min_u32_e32 v42, v7, v16
	v_max_u32_e32 v47, v12, v20
	v_min_u32_e32 v23, v12, v20
	v_max_u32_e32 v48, v6, v11
	v_min_u32_e32 v56, v6, v11
	s_cbranch_scc1 .LBB0_1186
; DI float key_val16(unsigned k) { const unsigned o = k >> 16; const unsigned short b = (unsigned short)((o & 0x8000u) ? (o & 0x7fffu) : (~o & 0xffffu)); return (float)__builtin_bit_cast(_Float16, b); }
; DI unsigned candkey(float s, int pos) { const unsigned b = __float_as_uint(s); const unsigned o = (b >> 31) ? ~b : (b ^ 0x80000000u); return (o & 0xffffff00u) | (unsigned)(255 - pos); }
; DI void phase10(const Params& P, char* smem) {
;     ...
;     float v1[16], v2[16]; unsigned W1[4] = {0u, 0u, 0u, 0u}, W2[4] = {0u, 0u, 0u, 0u};
; #pragma unroll
;     for (int k = 0; k < 16; ++k) {
;       v1[k] = key_val16(R1[k]); v2[k] = key_val16(R2[k]);
;       W1[k >> 2] |= (127u - (R1[k] & 127u)) << ((k & 3) * 8);
;       W2[k >> 2] |= (127u - (R2[k] & 127u)) << ((k & 3) * 8);
;     }
	v_lshlrev_b32_e32 v5, 8, v24
	v_lshlrev_b32_e32 v6, 16, v40
	v_and_b32_e32 v4, 0x7f, v35
	v_and_b32_e32 v5, 0x7f00, v5
	v_and_b32_e32 v6, 0x7f0000, v6
	v_or3_b32 v4, v5, v4, v6
	v_and_b32_sdwa v5, v46, s57 dst_sel:DWORD dst_unused:UNUSED_PAD src0_sel:WORD_1 src1_sel:DWORD
	v_xor_b32_sdwa v7, v46, v27 dst_sel:DWORD dst_unused:UNUSED_PAD src0_sel:WORD_1 src1_sel:DWORD
	v_cmp_gt_i32_e32 vcc, 0, v46
	v_and_b32_sdwa v6, v41, s57 dst_sel:DWORD dst_unused:UNUSED_PAD src0_sel:WORD_1 src1_sel:DWORD
	v_xor_b32_sdwa v8, v41, v27 dst_sel:DWORD dst_unused:UNUSED_PAD src0_sel:WORD_1 src1_sel:DWORD
	v_cndmask_b32_e32 v5, v7, v5, vcc
	v_cmp_gt_i32_e32 vcc, 0, v41
	v_xor_b32_sdwa v7, v39, v27 dst_sel:DWORD dst_unused:UNUSED_PAD src0_sel:WORD_1 src1_sel:DWORD
	v_xor_b32_sdwa v11, v36, v27 dst_sel:DWORD dst_unused:UNUSED_PAD src0_sel:WORD_1 src1_sel:DWORD
	v_cndmask_b32_e32 v6, v8, v6, vcc
	v_cvt_f32_f16_e32 v8, v5
	v_lshlrev_b32_e32 v5, 24, v41
	v_and_b32_e32 v5, 0x7f000000, v5
	v_cvt_f32_f16_e32 v12, v6
	v_bitop3_b32 v15, v4, s75, v5 bitop3:0x36
	v_and_b32_sdwa v4, v54, s57 dst_sel:DWORD dst_unused:UNUSED_PAD src0_sel:WORD_1 src1_sel:DWORD
	v_xor_b32_sdwa v6, v54, v27 dst_sel:DWORD dst_unused:UNUSED_PAD src0_sel:WORD_1 src1_sel:DWORD
	v_cmp_gt_i32_e32 vcc, 0, v54
	v_and_b32_sdwa v5, v39, s57 dst_sel:DWORD dst_unused:UNUSED_PAD src0_sel:WORD_1 src1_sel:DWORD
	v_xor_b32_sdwa v13, v24, v27 dst_sel:DWORD dst_unused:UNUSED_PAD src0_sel:WORD_1 src1_sel:DWORD
	v_cndmask_b32_e32 v4, v6, v4, vcc
	v_cmp_gt_i32_e32 vcc, 0, v39
	v_cvt_f32_f16_e32 v9, v4
	v_and_b32_sdwa v4, v52, s57 dst_sel:DWORD dst_unused:UNUSED_PAD src0_sel:WORD_1 src1_sel:DWORD
	v_cndmask_b32_e32 v5, v7, v5, vcc
	v_xor_b32_sdwa v6, v52, v27 dst_sel:DWORD dst_unused:UNUSED_PAD src0_sel:WORD_1 src1_sel:DWORD
	v_cmp_gt_i32_e32 vcc, 0, v52
	v_cvt_f32_f16_e32 v10, v5
	v_and_b32_sdwa v5, v40, s57 dst_sel:DWORD dst_unused:UNUSED_PAD src0_sel:WORD_1 src1_sel:DWORD
	v_xor_b32_sdwa v7, v40, v27 dst_sel:DWORD dst_unused:UNUSED_PAD src0_sel:WORD_1 src1_sel:DWORD
	v_cndmask_b32_e32 v4, v6, v4, vcc
	v_cmp_gt_i32_e32 vcc, 0, v40
	v_not_b32_sdwa v6, v25 dst_sel:DWORD dst_unused:UNUSED_PAD src0_sel:WORD_1
	v_cvt_f32_f16_e32 v21, v4
	v_cndmask_b32_e32 v5, v7, v5, vcc
	v_cvt_f32_f16_e32 v22, v5
	v_bfe_u32 v5, v25, 16, 15
	v_cmp_gt_i32_e32 vcc, 0, v25
	v_not_b32_sdwa v7, v38 dst_sel:DWORD dst_unused:UNUSED_PAD src0_sel:WORD_1
	v_and_b32_e32 v4, 0x7f, v39
	v_cndmask_b32_e32 v5, v6, v5, vcc
	v_cvt_f32_f16_e32 v14, v5
	v_bfe_u32 v5, v45, 16, 15
	v_not_b32_sdwa v6, v45 dst_sel:DWORD dst_unused:UNUSED_PAD src0_sel:WORD_1
	v_cmp_gt_i32_e32 vcc, 0, v45
	s_movk_i32 s0, 0xfe
	v_xor_b32_sdwa v57, v50, v27 dst_sel:DWORD dst_unused:UNUSED_PAD src0_sel:WORD_1 src1_sel:DWORD
	v_cndmask_b32_e32 v5, v6, v5, vcc
	v_bfe_u32 v6, v38, 16, 15
	v_cmp_gt_i32_e32 vcc, 0, v38
	v_cvt_f32_f16_e32 v20, v5
	v_lshlrev_b32_e32 v5, 8, v25
	v_cndmask_b32_e32 v6, v7, v6, vcc
	v_cvt_f32_f16_e32 v16, v6
	v_bfe_u32 v6, v53, 16, 15
	v_not_b32_sdwa v7, v53 dst_sel:DWORD dst_unused:UNUSED_PAD src0_sel:WORD_1
	v_cmp_gt_i32_e32 vcc, 0, v53
	v_and_b32_e32 v5, 0x7f00, v5
	v_xor_b32_sdwa v81, v32, v27 dst_sel:DWORD dst_unused:UNUSED_PAD src0_sel:WORD_1 src1_sel:DWORD
	v_cndmask_b32_e32 v6, v7, v6, vcc
	v_cvt_f32_f16_e32 v25, v6
	v_lshlrev_b32_e32 v6, 16, v38
	v_and_b32_e32 v6, 0x7f0000, v6
	v_or3_b32 v4, v5, v4, v6
	v_and_b32_sdwa v5, v49, s57 dst_sel:DWORD dst_unused:UNUSED_PAD src0_sel:WORD_1 src1_sel:DWORD
	v_xor_b32_sdwa v7, v49, v27 dst_sel:DWORD dst_unused:UNUSED_PAD src0_sel:WORD_1 src1_sel:DWORD
	v_cmp_gt_i32_e32 vcc, 0, v49
	v_and_b32_sdwa v6, v36, s57 dst_sel:DWORD dst_unused:UNUSED_PAD src0_sel:WORD_1 src1_sel:DWORD
	v_xor_b32_sdwa v38, v35, v27 dst_sel:DWORD dst_unused:UNUSED_PAD src0_sel:WORD_1 src1_sel:DWORD
	v_cndmask_b32_e32 v5, v7, v5, vcc
	v_cmp_gt_i32_e32 vcc, 0, v36
	s_nop 1
	v_cndmask_b32_e32 v7, v11, v6, vcc
	v_cvt_f32_f16_e32 v18, v7
	v_and_b32_sdwa v7, v24, s57 dst_sel:DWORD dst_unused:UNUSED_PAD src0_sel:WORD_1 src1_sel:DWORD
	v_cmp_gt_i32_e32 vcc, 0, v24
	v_cvt_f32_f16_e32 v6, v5
	v_and_b32_sdwa v5, v44, s57 dst_sel:DWORD dst_unused:UNUSED_PAD src0_sel:WORD_1 src1_sel:DWORD
	v_xor_b32_sdwa v11, v44, v27 dst_sel:DWORD dst_unused:UNUSED_PAD src0_sel:WORD_1 src1_sel:DWORD
	v_cndmask_b32_e32 v7, v13, v7, vcc
	v_cmp_gt_i32_e32 vcc, 0, v44
	v_cvt_f32_f16_e32 v64, v7
	v_lshlrev_b32_e32 v7, 16, v31
	v_cndmask_b32_e32 v5, v11, v5, vcc
	v_cvt_f32_f16_e32 v24, v5
	v_lshlrev_b32_e32 v5, 24, v36
	v_and_b32_e32 v5, 0x7f000000, v5
	v_bitop3_b32 v17, v4, s75, v5 bitop3:0x36
	v_lshlrev_b32_e32 v5, 8, v32
	v_and_b32_e32 v4, 0x7f, v33
	v_and_b32_e32 v5, 0x7f00, v5
	v_and_b32_e32 v7, 0x7f0000, v7
	v_or3_b32 v4, v5, v4, v7
	v_lshlrev_b32_e32 v5, 24, v30
	v_and_b32_e32 v5, 0x7f000000, v5
	v_bitop3_b32 v19, v4, s75, v5 bitop3:0x36
	v_lshlrev_b32_e32 v5, 8, v1
	v_and_b32_e32 v11, 0x7f00, v5
	v_and_b32_sdwa v5, v55, s57 dst_sel:DWORD dst_unused:UNUSED_PAD src0_sel:WORD_1 src1_sel:DWORD
	v_xor_b32_sdwa v13, v55, v27 dst_sel:DWORD dst_unused:UNUSED_PAD src0_sel:WORD_1 src1_sel:DWORD
	v_cmp_gt_i32_e32 vcc, 0, v55
	v_and_b32_sdwa v7, v34, s57 dst_sel:DWORD dst_unused:UNUSED_PAD src0_sel:WORD_1 src1_sel:DWORD
	v_xor_b32_sdwa v36, v34, v27 dst_sel:DWORD dst_unused:UNUSED_PAD src0_sel:WORD_1 src1_sel:DWORD
	v_cndmask_b32_e32 v5, v13, v5, vcc
	v_cmp_gt_i32_e32 vcc, 0, v34
	v_and_b32_e32 v4, 0x7f, v3
	s_nop 0
	v_cndmask_b32_e32 v13, v36, v7, vcc
	v_cvt_f32_f16_e32 v7, v5
	v_cvt_f32_f16_e32 v5, v13
	v_bfe_u32 v13, v48, 16, 15
	v_not_b32_sdwa v36, v48 dst_sel:DWORD dst_unused:UNUSED_PAD src0_sel:WORD_1
	v_cmp_gt_i32_e32 vcc, 0, v48
	s_nop 1
	v_cndmask_b32_e32 v13, v36, v13, vcc
; DI float key_val16(unsigned k) { const unsigned o = k >> 16; const unsigned short b = (unsigned short)((o & 0x8000u) ? (o & 0x7fffu) : (~o & 0xffffu)); return (float)__builtin_bit_cast(_Float16, b); }
; DI unsigned candkey(float s, int pos) { const unsigned b = __float_as_uint(s); const unsigned o = (b >> 31) ? ~b : (b ^ 0x80000000u); return (o & 0xffffff00u) | (unsigned)(255 - pos); }
; DI void phase10(const Params& P, char* smem) {
;     ...
;     float v1[16], v2[16]; unsigned W1[4] = {0u, 0u, 0u, 0u}, W2[4] = {0u, 0u, 0u, 0u};
; #pragma unroll
;     for (int k = 0; k < 16; ++k) {
;       v1[k] = key_val16(R1[k]); v2[k] = key_val16(R2[k]);
;       W1[k >> 2] |= (127u - (R1[k] & 127u)) << ((k & 3) * 8);
;       W2[k >> 2] |= (127u - (R2[k] & 127u)) << ((k & 3) * 8);
;     }
;     unsigned C0[16], C1[16], C2[16], C3[16];
;     C0[0] = candkey(v1[0] + v2[0], 0);
;     C0[1] = candkey(v1[0] + v2[1], 1);
;     C0[2] = candkey(v1[0] + v2[2], 2);
;     C0[3] = candkey(v1[0] + v2[3], 3);
;     C0[4] = candkey(v1[0] + v2[4], 4);
;     C0[5] = candkey(v1[0] + v2[5], 5);
;     C0[6] = candkey(v1[0] + v2[6], 6);
;     C0[7] = candkey(v1[0] + v2[7], 7);
;     C0[8] = candkey(v1[0] + v2[8], 8);
;     C0[9] = candkey(v1[0] + v2[9], 9);
;     C0[10] = candkey(v1[0] + v2[10], 10);
;     C0[11] = candkey(v1[0] + v2[11], 11);
;     C0[12] = candkey(v1[0] + v2[12], 12);
;     C0[13] = candkey(v1[0] + v2[13], 13);
;     C0[14] = candkey(v1[0] + v2[14], 14);
;     C0[15] = candkey(v1[0] + v2[15], 15);
;     C1[0] = candkey(v1[1] + v2[0], 16);
;     C1[1] = candkey(v1[1] + v2[1], 17);
;     C1[2] = candkey(v1[1] + v2[2], 18);
;     C1[3] = candkey(v1[1] + v2[3], 19);
;     C1[4] = candkey(v1[1] + v2[4], 20);
;     C1[5] = candkey(v1[1] + v2[5], 21);
;     C1[6] = candkey(v1[1] + v2[6], 22);
;     C1[7] = candkey(v1[1] + v2[7], 23);
;     C1[8] = candkey(v1[2] + v2[0], 32);
;     C1[9] = candkey(v1[2] + v2[1], 33);
;     C1[10] = candkey(v1[2] + v2[2], 34);
;     C1[11] = candkey(v1[2] + v2[3], 35);
;     C1[12] = candkey(v1[2] + v2[4], 36);
;     C1[13] = candkey(v1[3] + v2[0], 48);
;     C1[14] = candkey(v1[3] + v2[1], 49);
;     C1[15] = candkey(v1[3] + v2[2], 50);
	v_cvt_f32_f16_e32 v67, v13
	v_lshlrev_b32_e32 v13, 16, v34
	v_and_b32_e32 v13, 0x7f0000, v13
	v_or3_b32 v11, v11, v4, v13
	v_bfe_u32 v4, v37, 16, 15
	v_not_b32_sdwa v13, v37 dst_sel:DWORD dst_unused:UNUSED_PAD src0_sel:WORD_1
	v_cmp_gt_i32_e32 vcc, 0, v37
	v_xor_b32_sdwa v36, v56, v27 dst_sel:DWORD dst_unused:UNUSED_PAD src0_sel:WORD_1 src1_sel:DWORD
	v_and_b32_sdwa v34, v35, s57 dst_sel:DWORD dst_unused:UNUSED_PAD src0_sel:WORD_1 src1_sel:DWORD
	v_cndmask_b32_e32 v4, v13, v4, vcc
	v_and_b32_sdwa v13, v56, s57 dst_sel:DWORD dst_unused:UNUSED_PAD src0_sel:WORD_1 src1_sel:DWORD
	v_cmp_gt_i32_e32 vcc, 0, v56
	v_cvt_f32_f16_e32 v4, v4
	s_nop 0
	v_cndmask_b32_e32 v13, v36, v13, vcc
	v_cmp_gt_i32_e32 vcc, 0, v35
	v_cvt_f32_f16_e32 v66, v13
	v_lshlrev_b32_e32 v13, 24, v37
	v_cndmask_b32_e32 v34, v38, v34, vcc
	v_cvt_f32_f16_e32 v68, v34
	v_and_b32_e32 v13, 0x7f000000, v13
	v_bitop3_b32 v34, v11, s75, v13 bitop3:0x36
	v_pk_add_f32 v[36:37], v[68:69], v[6:7] op_sel_hi:[0,1]
	v_cmp_lt_i32_e32 vcc, -1, v37
	v_pk_add_f32 v[38:39], v[68:69], v[8:9] op_sel_hi:[0,1]
	v_and_b32_e32 v13, 0xffffff00, v36
	v_cndmask_b32_e32 v11, v28, v29, vcc
	v_cmp_lt_i32_e32 vcc, -1, v36
	v_bitop3_b32 v35, v11, s3, v37 bitop3:0xde
	v_pk_add_f32 v[40:41], v[68:69], v[20:21] op_sel_hi:[0,1]
	v_cndmask_b32_e32 v11, v28, v29, vcc
	v_cmp_lt_i32_e32 vcc, -1, v39
	v_bitop3_b32 v36, v11, s0, v13 bitop3:0xde
	v_and_b32_e32 v13, 0xffffff00, v39
	v_cndmask_b32_e32 v11, v28, v29, vcc
	s_movk_i32 s0, 0xfd
	v_cmp_lt_i32_e32 vcc, -1, v38
	v_bitop3_b32 v37, v11, s0, v13 bitop3:0xde
	v_and_b32_e32 v13, 0xffffff00, v38
	v_cndmask_b32_e32 v11, v28, v29, vcc
	s_movk_i32 s0, 0xfc
	v_cmp_lt_i32_e32 vcc, -1, v41
	v_bitop3_b32 v38, v11, s0, v13 bitop3:0xde
	v_and_b32_e32 v13, 0xffffff00, v41
	v_cndmask_b32_e32 v11, v28, v29, vcc
	s_movk_i32 s0, 0xfb
	v_cmp_lt_i32_e32 vcc, -1, v40
	v_pk_add_f32 v[58:59], v[68:69], v[24:25] op_sel_hi:[0,1]
	v_bitop3_b32 v39, v11, s0, v13 bitop3:0xde
	v_cndmask_b32_e32 v11, v28, v29, vcc
	v_and_b32_e32 v13, 0xffffff00, v40
	s_movk_i32 s0, 0xfa
	v_cmp_lt_i32_e32 vcc, -1, v59
	v_bitop3_b32 v40, v11, s0, v13 bitop3:0xde
	v_and_b32_e32 v13, 0xffffff00, v59
	v_cndmask_b32_e32 v11, v28, v29, vcc
	s_movk_i32 s0, 0xf9
	v_bitop3_b32 v41, v11, s0, v13 bitop3:0xde
	v_and_b32_sdwa v11, v50, s57 dst_sel:DWORD dst_unused:UNUSED_PAD src0_sel:WORD_1 src1_sel:DWORD
	v_cmp_gt_i32_e32 vcc, 0, v50
	v_and_b32_sdwa v13, v43, s57 dst_sel:DWORD dst_unused:UNUSED_PAD src0_sel:WORD_1 src1_sel:DWORD
	v_xor_b32_sdwa v59, v43, v27 dst_sel:DWORD dst_unused:UNUSED_PAD src0_sel:WORD_1 src1_sel:DWORD
	v_cndmask_b32_e32 v11, v57, v11, vcc
	v_cmp_gt_i32_e32 vcc, 0, v43
	v_cvt_f32_f16_e32 v61, v11
	s_movk_i32 s0, 0xf8
	v_cndmask_b32_e32 v13, v59, v13, vcc
	v_cvt_f32_f16_e32 v60, v13
	v_cmp_lt_i32_e32 vcc, -1, v58
	v_and_b32_e32 v13, 0xffffff00, v58
	v_xor_b32_sdwa v59, v51, v27 dst_sel:DWORD dst_unused:UNUSED_PAD src0_sel:WORD_1 src1_sel:DWORD
	v_pk_add_f32 v[60:61], v[68:69], v[60:61] op_sel_hi:[0,1]
	v_cndmask_b32_e32 v11, v28, v29, vcc
	v_cmp_lt_i32_e32 vcc, -1, v61
	v_bitop3_b32 v57, v11, s0, v13 bitop3:0xde
	v_and_b32_e32 v13, 0xffffff00, v61
	v_cndmask_b32_e32 v11, v28, v29, vcc
	s_movk_i32 s0, 0xf7
	v_bitop3_b32 v58, v11, s0, v13 bitop3:0xde
	v_and_b32_sdwa v11, v51, s57 dst_sel:DWORD dst_unused:UNUSED_PAD src0_sel:WORD_1 src1_sel:DWORD
	v_cmp_gt_i32_e32 vcc, 0, v51
	v_and_b32_sdwa v13, v42, s57 dst_sel:DWORD dst_unused:UNUSED_PAD src0_sel:WORD_1 src1_sel:DWORD
	v_xor_b32_sdwa v61, v42, v27 dst_sel:DWORD dst_unused:UNUSED_PAD src0_sel:WORD_1 src1_sel:DWORD
	v_cndmask_b32_e32 v11, v59, v11, vcc
	v_cmp_gt_i32_e32 vcc, 0, v42
	v_cvt_f32_f16_e32 v63, v11
	s_movk_i32 s0, 0xf6
	v_cndmask_b32_e32 v13, v61, v13, vcc
	v_cvt_f32_f16_e32 v62, v13
	v_cmp_lt_i32_e32 vcc, -1, v60
	v_and_b32_e32 v13, 0xffffff00, v60
	v_xor_b32_sdwa v61, v47, v27 dst_sel:DWORD dst_unused:UNUSED_PAD src0_sel:WORD_1 src1_sel:DWORD
	v_pk_add_f32 v[62:63], v[68:69], v[62:63] op_sel_hi:[0,1]
	v_cndmask_b32_e32 v11, v28, v29, vcc
	v_cmp_lt_i32_e32 vcc, -1, v63
	v_bitop3_b32 v59, v11, s0, v13 bitop3:0xde
	v_and_b32_e32 v13, 0xffffff00, v63
	v_cndmask_b32_e32 v11, v28, v29, vcc
	s_movk_i32 s0, 0xf5
	v_bitop3_b32 v60, v11, s0, v13 bitop3:0xde
	v_and_b32_sdwa v11, v47, s57 dst_sel:DWORD dst_unused:UNUSED_PAD src0_sel:WORD_1 src1_sel:DWORD
	v_cmp_gt_i32_e32 vcc, 0, v47
	v_and_b32_sdwa v13, v23, s57 dst_sel:DWORD dst_unused:UNUSED_PAD src0_sel:WORD_1 src1_sel:DWORD
	v_xor_b32_sdwa v63, v23, v27 dst_sel:DWORD dst_unused:UNUSED_PAD src0_sel:WORD_1 src1_sel:DWORD
	v_cndmask_b32_e32 v11, v61, v11, vcc
	v_cmp_gt_i32_e32 vcc, 0, v23
	v_cvt_f32_f16_e32 v71, v11
	s_movk_i32 s0, 0xf4
	v_cndmask_b32_e32 v13, v63, v13, vcc
	v_cvt_f32_f16_e32 v70, v13
	v_cmp_lt_i32_e32 vcc, -1, v62
	v_and_b32_e32 v13, 0xffffff00, v62
	v_pk_add_f32 v[66:67], v[68:69], v[66:67] op_sel_hi:[0,1]
	v_pk_add_f32 v[70:71], v[68:69], v[70:71] op_sel_hi:[0,1]
	v_cndmask_b32_e32 v11, v28, v29, vcc
	v_cmp_lt_i32_e32 vcc, -1, v71
	v_bitop3_b32 v61, v11, s0, v13 bitop3:0xde
	v_and_b32_e32 v13, 0xffffff00, v71
	v_cndmask_b32_e32 v11, v28, v29, vcc
	s_movk_i32 s0, 0xf3
	v_cmp_lt_i32_e32 vcc, -1, v70
	v_bitop3_b32 v62, v11, s0, v13 bitop3:0xde
	v_and_b32_e32 v13, 0xffffff00, v70
	v_cndmask_b32_e32 v11, v28, v29, vcc
	s_movk_i32 s0, 0xf2
	v_cmp_lt_i32_e32 vcc, -1, v67
	v_bitop3_b32 v63, v11, s0, v13 bitop3:0xde
	v_and_b32_e32 v13, 0xffffff00, v67
	v_cndmask_b32_e32 v11, v28, v29, vcc
	s_movk_i32 s0, 0xf1
	v_bitop3_b32 v65, v11, s0, v13 bitop3:0xde
	v_cmp_lt_i32_e32 vcc, -1, v66
	v_and_b32_e32 v13, 0xffffff00, v66
	v_pk_add_f32 v[66:67], v[64:65], v[6:7] op_sel_hi:[0,1]
; DI unsigned candkey(float s, int pos) { const unsigned b = __float_as_uint(s); const unsigned o = (b >> 31) ? ~b : (b ^ 0x80000000u); return (o & 0xffffff00u) | (unsigned)(255 - pos); }
; DI void phase10(const Params& P, char* smem) {
;     ...
;     C0[0] = candkey(v1[0] + v2[0], 0);
;     C0[1] = candkey(v1[0] + v2[1], 1);
;     C0[2] = candkey(v1[0] + v2[2], 2);
;     C0[3] = candkey(v1[0] + v2[3], 3);
;     C0[4] = candkey(v1[0] + v2[4], 4);
;     C0[5] = candkey(v1[0] + v2[5], 5);
;     C0[6] = candkey(v1[0] + v2[6], 6);
;     C0[7] = candkey(v1[0] + v2[7], 7);
;     C0[8] = candkey(v1[0] + v2[8], 8);
;     C0[9] = candkey(v1[0] + v2[9], 9);
;     C0[10] = candkey(v1[0] + v2[10], 10);
;     C0[11] = candkey(v1[0] + v2[11], 11);
;     C0[12] = candkey(v1[0] + v2[12], 12);
;     C0[13] = candkey(v1[0] + v2[13], 13);
;     C0[14] = candkey(v1[0] + v2[14], 14);
;     C0[15] = candkey(v1[0] + v2[15], 15);
;     C1[0] = candkey(v1[1] + v2[0], 16);
;     C1[1] = candkey(v1[1] + v2[1], 17);
;     C1[2] = candkey(v1[1] + v2[2], 18);
;     C1[3] = candkey(v1[1] + v2[3], 19);
;     C1[4] = candkey(v1[1] + v2[4], 20);
;     C1[5] = candkey(v1[1] + v2[5], 21);
;     C1[6] = candkey(v1[1] + v2[6], 22);
;     C1[7] = candkey(v1[1] + v2[7], 23);
;     C1[8] = candkey(v1[2] + v2[0], 32);
;     C1[9] = candkey(v1[2] + v2[1], 33);
;     C1[10] = candkey(v1[2] + v2[2], 34);
;     C1[11] = candkey(v1[2] + v2[3], 35);
;     C1[12] = candkey(v1[2] + v2[4], 36);
;     C1[13] = candkey(v1[3] + v2[0], 48);
;     C1[14] = candkey(v1[3] + v2[1], 49);
;     C1[15] = candkey(v1[3] + v2[2], 50);
;     C2[0] = candkey(v1[3] + v2[3], 51);
;     C2[1] = candkey(v1[4] + v2[0], 64);
;     C2[2] = candkey(v1[4] + v2[1], 65);
;     C2[3] = candkey(v1[4] + v2[2], 66);
;     C2[4] = candkey(v1[5] + v2[0], 80);
;     C2[5] = candkey(v1[5] + v2[1], 81);
;     C2[6] = candkey(v1[6] + v2[0], 96);
;     C2[7] = candkey(v1[6] + v2[1], 97);
;     C2[8] = candkey(v1[7] + v2[0], 112);
;     C2[9] = candkey(v1[7] + v2[1], 113);
;     C2[10] = candkey(v1[8] + v2[0], 128);
;     C2[11] = candkey(v1[9] + v2[0], 144);
;     C2[12] = candkey(v1[10] + v2[0], 160);
;     C2[13] = candkey(v1[11] + v2[0], 176);
;     C2[14] = candkey(v1[12] + v2[0], 192);
;     C2[15] = candkey(v1[13] + v2[0], 208);
;     C3[0] = candkey(v1[14] + v2[0], 224);
;     C3[1] = candkey(v1[15] + v2[0], 240);
	v_cndmask_b32_e32 v11, v28, v29, vcc
	s_movk_i32 s0, 0xf0
	v_cmp_lt_i32_e32 vcc, -1, v67
	v_bitop3_b32 v68, v11, s0, v13 bitop3:0xde
	v_and_b32_e32 v13, 0xffffff00, v67
	v_cndmask_b32_e32 v11, v28, v29, vcc
	s_movk_i32 s0, 0xef
	v_bitop3_b32 v69, v11, s0, v13 bitop3:0xde
	v_cmp_lt_i32_e32 vcc, -1, v66
	v_and_b32_e32 v13, 0xffffff00, v66
	v_pk_add_f32 v[66:67], v[64:65], v[8:9] op_sel_hi:[0,1]
	v_cndmask_b32_e32 v11, v28, v29, vcc
	s_movk_i32 s0, 0xee
	v_cmp_lt_i32_e32 vcc, -1, v67
	v_bitop3_b32 v70, v11, s0, v13 bitop3:0xde
	v_and_b32_e32 v13, 0xffffff00, v67
	v_cndmask_b32_e32 v11, v28, v29, vcc
	s_movk_i32 s0, 0xed
	v_bitop3_b32 v71, v11, s0, v13 bitop3:0xde
	v_cmp_lt_i32_e32 vcc, -1, v66
	v_and_b32_e32 v13, 0xffffff00, v66
	v_pk_add_f32 v[66:67], v[64:65], v[20:21] op_sel_hi:[0,1]
	v_cndmask_b32_e32 v11, v28, v29, vcc
	s_movk_i32 s0, 0xec
	v_cmp_lt_i32_e32 vcc, -1, v67
	v_bitop3_b32 v72, v11, s0, v13 bitop3:0xde
	v_and_b32_e32 v13, 0xffffff00, v67
	v_cndmask_b32_e32 v11, v28, v29, vcc
	s_movk_i32 s0, 0xeb
	v_cmp_lt_i32_e32 vcc, -1, v66
	v_pk_add_f32 v[24:25], v[64:65], v[24:25] op_sel_hi:[0,1]
	v_bitop3_b32 v67, v11, s0, v13 bitop3:0xde
	v_cndmask_b32_e32 v11, v28, v29, vcc
	v_and_b32_e32 v13, 0xffffff00, v66
	s_movk_i32 s0, 0xea
	v_cmp_lt_i32_e32 vcc, -1, v25
	v_bitop3_b32 v66, v11, s0, v13 bitop3:0xde
	v_and_b32_e32 v13, 0xffffff00, v25
	v_cndmask_b32_e32 v11, v28, v29, vcc
	s_movk_i32 s0, 0xe9
	v_bitop3_b32 v64, v11, s0, v13 bitop3:0xde
	v_cmp_lt_i32_e32 vcc, -1, v24
	v_and_b32_e32 v13, 0xffffff00, v24
	v_pk_add_f32 v[24:25], v[22:23], v[6:7] op_sel_hi:[0,1]
	v_cndmask_b32_e32 v11, v28, v29, vcc
	v_cmp_lt_i32_e32 vcc, -1, v25
	v_bitop3_b32 v73, v11, s92, v13 bitop3:0xde
	v_and_b32_e32 v13, 0xffffff00, v25
	v_cndmask_b32_e32 v11, v28, v29, vcc
	v_bitop3_b32 v74, v11, s93, v13 bitop3:0xde
	v_cmp_lt_i32_e32 vcc, -1, v24
	v_and_b32_e32 v13, 0xffffff00, v24
	v_pk_add_f32 v[24:25], v[22:23], v[8:9] op_sel_hi:[0,1]
	v_cndmask_b32_e32 v11, v28, v29, vcc
	v_cmp_lt_i32_e32 vcc, -1, v25
	v_bitop3_b32 v75, v11, s94, v13 bitop3:0xde
	v_and_b32_e32 v13, 0xffffff00, v25
	v_cndmask_b32_e32 v11, v28, v29, vcc
	v_cmp_lt_i32_e32 vcc, -1, v24
	v_bitop3_b32 v76, v11, s95, v13 bitop3:0xde
	v_and_b32_e32 v13, 0xffffff00, v24
	v_cndmask_b32_e32 v11, v28, v29, vcc
	v_bitop3_b32 v77, v11, s96, v13 bitop3:0xde
	v_mov_b32_e32 v13, v22
	v_mov_b32_e32 v20, v7
	v_pk_add_f32 v[20:21], v[12:13], v[20:21]
	s_movk_i32 s0, 0x7f
	v_cmp_lt_i32_e32 vcc, -1, v21
	v_and_b32_e32 v13, 0xffffff00, v21
	v_mov_b32_e32 v21, v6
	v_cndmask_b32_e32 v11, v28, v29, vcc
	v_bitop3_b32 v22, v11, s97, v13 bitop3:0xde
	v_cmp_lt_i32_e32 vcc, -1, v20
	v_and_b32_e32 v13, 0xffffff00, v20
	v_mov_b32_e32 v20, v9
	v_pk_add_f32 v[24:25], v[12:13], v[20:21] op_sel_hi:[0,1]
	v_cndmask_b32_e32 v11, v28, v29, vcc
	v_cmp_lt_i32_e32 vcc, -1, v25
	v_bitop3_b32 v78, v11, s4, v13 bitop3:0xde
	v_and_b32_e32 v11, 0xffffff00, v25
	v_cndmask_b32_e32 v9, v28, v29, vcc
	v_cmp_lt_i32_e32 vcc, -1, v24
	v_bitop3_b32 v25, v9, s5, v11 bitop3:0xde
	v_and_b32_e32 v11, 0xffffff00, v24
	v_cndmask_b32_e32 v9, v28, v29, vcc
	v_bitop3_b32 v24, v9, s80, v11 bitop3:0xde
	v_mov_b32_e32 v11, v12
	v_mov_b32_e32 v12, v7
	v_mov_b32_e32 v13, v8
	v_pk_add_f32 v[8:9], v[10:11], v[12:13]
	s_nop 0
	v_cmp_lt_i32_e32 vcc, -1, v9
	v_and_b32_e32 v9, 0xffffff00, v9
	s_nop 0
	v_cndmask_b32_e32 v11, v28, v29, vcc
	v_cmp_lt_i32_e32 vcc, -1, v8
	v_bitop3_b32 v12, v11, s81, v9 bitop3:0xde
	v_and_b32_e32 v8, 0xffffff00, v8
	v_cndmask_b32_e32 v9, v28, v29, vcc
	v_bitop3_b32 v13, v9, s22, v8 bitop3:0xde
	v_pk_add_f32 v[8:9], v[10:11], v[20:21] op_sel_hi:[0,1]
	v_cmp_lt_i32_e32 vcc, -1, v9
	v_and_b32_e32 v9, 0xffffff00, v9
	v_xor_b32_sdwa v11, v33, v27 dst_sel:DWORD dst_unused:UNUSED_PAD src0_sel:WORD_1 src1_sel:DWORD
	v_cndmask_b32_e32 v10, v28, v29, vcc
	v_cmp_lt_i32_e32 vcc, -1, v8
	v_bitop3_b32 v20, v10, s23, v9 bitop3:0xde
	v_and_b32_e32 v8, 0xffffff00, v8
	v_cndmask_b32_e32 v9, v28, v29, vcc
	v_bitop3_b32 v21, v9, s82, v8 bitop3:0xde
	v_pk_add_f32 v[8:9], v[14:15], v[6:7] op_sel_hi:[0,1]
	v_cmp_lt_i32_e32 vcc, -1, v9
	v_and_b32_e32 v9, 0xffffff00, v9
	v_max_u32_e32 v84, v12, v13
	v_cndmask_b32_e32 v10, v28, v29, vcc
	v_cmp_lt_i32_e32 vcc, -1, v8
	v_bitop3_b32 v14, v10, s83, v9 bitop3:0xde
	v_and_b32_e32 v8, 0xffffff00, v8
	v_cndmask_b32_e32 v9, v28, v29, vcc
	v_bitop3_b32 v79, v9, s44, v8 bitop3:0xde
	v_pk_add_f32 v[8:9], v[16:17], v[6:7] op_sel_hi:[0,1]
	v_cmp_lt_i32_e32 vcc, -1, v9
	v_and_b32_e32 v9, 0xffffff00, v9
	v_min_u32_e32 v12, v12, v13
	v_cndmask_b32_e32 v10, v28, v29, vcc
	v_cmp_lt_i32_e32 vcc, -1, v8
	v_bitop3_b32 v16, v10, s45, v9 bitop3:0xde
	v_and_b32_e32 v8, 0xffffff00, v8
	v_cndmask_b32_e32 v9, v28, v29, vcc
	v_bitop3_b32 v80, v9, s33, v8 bitop3:0xde
	v_pk_add_f32 v[8:9], v[18:19], v[6:7] op_sel_hi:[0,1]
	v_cmp_lt_i32_e32 vcc, -1, v9
	v_and_b32_e32 v9, 0xffffff00, v9
	v_and_b32_sdwa v10, v32, s57 dst_sel:DWORD dst_unused:UNUSED_PAD src0_sel:WORD_1 src1_sel:DWORD
	v_cndmask_b32_e32 v6, v28, v29, vcc
	v_cmp_lt_i32_e32 vcc, -1, v8
	v_bitop3_b32 v18, v6, s87, v9 bitop3:0xde
	v_and_b32_sdwa v9, v33, s57 dst_sel:DWORD dst_unused:UNUSED_PAD src0_sel:WORD_1 src1_sel:DWORD
	v_cndmask_b32_e32 v6, v28, v29, vcc
	v_cmp_gt_i32_e32 vcc, 0, v33
	v_and_b32_e32 v8, 0xffffff00, v8
	v_xor_b32_sdwa v33, v30, v27 dst_sel:DWORD dst_unused:UNUSED_PAD src0_sel:WORD_1 src1_sel:DWORD
	v_cndmask_b32_e32 v9, v11, v9, vcc
	v_cmp_gt_i32_e32 vcc, 0, v32
	v_cvt_f32_f16_e32 v11, v9
	v_bitop3_b32 v32, v6, s2, v8 bitop3:0xde
	v_cndmask_b32_e32 v10, v81, v10, vcc
	v_cvt_f32_f16_e32 v10, v10
	v_mov_b32_e32 v6, v7
	v_max_u32_e32 v13, v20, v21
	v_min_u32_e32 v20, v20, v21
; DI unsigned candkey(float s, int pos) { const unsigned b = __float_as_uint(s); const unsigned o = (b >> 31) ? ~b : (b ^ 0x80000000u); return (o & 0xffffff00u) | (unsigned)(255 - pos); }
; DI void phase10(const Params& P, char* smem) {
;     ...
;     C2[1] = candkey(v1[4] + v2[0], 64);
;     C2[2] = candkey(v1[4] + v2[1], 65);
;     C2[3] = candkey(v1[4] + v2[2], 66);
;     C2[4] = candkey(v1[5] + v2[0], 80);
;     C2[5] = candkey(v1[5] + v2[1], 81);
;     C2[6] = candkey(v1[6] + v2[0], 96);
;     C2[7] = candkey(v1[6] + v2[1], 97);
;     C2[8] = candkey(v1[7] + v2[0], 112);
;     C2[9] = candkey(v1[7] + v2[1], 113);
;     C2[10] = candkey(v1[8] + v2[0], 128);
;     C2[11] = candkey(v1[9] + v2[0], 144);
;     C2[12] = candkey(v1[10] + v2[0], 160);
;     C2[13] = candkey(v1[11] + v2[0], 176);
;     C2[14] = candkey(v1[12] + v2[0], 192);
;     C2[15] = candkey(v1[13] + v2[0], 208);
;     C3[0] = candkey(v1[14] + v2[0], 224);
;     C3[1] = candkey(v1[15] + v2[0], 240);
;     C3[2] = 0u;
;     C3[3] = 0u;
;     C3[4] = 0u;
;     C3[5] = 0u;
;     C3[6] = 0u;
;     C3[7] = 0u;
;     C3[8] = 0u;
;     C3[9] = 0u;
;     C3[10] = 0u;
;     C3[11] = 0u;
;     C3[12] = 0u;
;     C3[13] = 0u;
;     C3[14] = 0u;
;     C3[15] = 0u;
;     SORT16(C1) SORT16(C2) SORT16(C3)
	v_pk_add_f32 v[8:9], v[6:7], v[10:11] op_sel_hi:[0,1]
	v_cmp_lt_i32_e32 vcc, -1, v9
	v_and_b32_e32 v9, 0xffffff00, v9
	v_xor_b32_sdwa v11, v31, v27 dst_sel:DWORD dst_unused:UNUSED_PAD src0_sel:WORD_1 src1_sel:DWORD
	v_cndmask_b32_e32 v7, v28, v29, vcc
	v_bitop3_b32 v7, v7, s0, v9 bitop3:0xde
	v_and_b32_sdwa v9, v31, s57 dst_sel:DWORD dst_unused:UNUSED_PAD src0_sel:WORD_1 src1_sel:DWORD
	v_cmp_gt_i32_e32 vcc, 0, v31
	v_and_b32_sdwa v10, v30, s57 dst_sel:DWORD dst_unused:UNUSED_PAD src0_sel:WORD_1 src1_sel:DWORD
	v_pk_add_f32 v[4:5], v[4:5], v[6:7] op_sel_hi:[1,0]
	v_cndmask_b32_e32 v9, v11, v9, vcc
	v_cmp_gt_i32_e32 vcc, 0, v30
	v_cvt_f32_f16_e32 v11, v9
	v_max_u32_e32 v21, v14, v79
	v_cndmask_b32_e32 v10, v33, v10, vcc
	v_cvt_f32_f16_e32 v10, v10
	v_cmp_lt_i32_e32 vcc, -1, v8
	v_and_b32_e32 v8, 0xffffff00, v8
	v_xor_b32_sdwa v33, v1, v27 dst_sel:DWORD dst_unused:UNUSED_PAD src0_sel:WORD_1 src1_sel:DWORD
	v_cndmask_b32_e32 v9, v28, v29, vcc
	v_bitop3_b32 v30, v9, s88, v8 bitop3:0xde
	v_pk_add_f32 v[8:9], v[6:7], v[10:11] op_sel_hi:[0,1]
	v_cmp_lt_i32_e32 vcc, -1, v9
	v_and_b32_e32 v9, 0xffffff00, v9
	v_xor_b32_sdwa v11, v3, v27 dst_sel:DWORD dst_unused:UNUSED_PAD src0_sel:WORD_1 src1_sel:DWORD
	v_cndmask_b32_e32 v10, v28, v29, vcc
	v_bitop3_b32 v31, v10, s89, v9 bitop3:0xde
	v_and_b32_sdwa v9, v3, s57 dst_sel:DWORD dst_unused:UNUSED_PAD src0_sel:WORD_1 src1_sel:DWORD
	v_cmp_gt_i32_e32 vcc, 0, v3
	v_and_b32_sdwa v10, v1, s57 dst_sel:DWORD dst_unused:UNUSED_PAD src0_sel:WORD_1 src1_sel:DWORD
	v_min_u32_e32 v14, v14, v79
	v_cndmask_b32_e32 v3, v11, v9, vcc
	v_cmp_gt_i32_e32 vcc, 0, v1
	v_cvt_f32_f16_e32 v11, v3
	v_and_b32_e32 v3, 0xffffff00, v8
	v_cndmask_b32_e32 v1, v33, v10, vcc
	v_cvt_f32_f16_e32 v10, v1
	v_cmp_lt_i32_e32 vcc, -1, v8
	v_max_u32_e32 v33, v67, v66
	v_min_u32_e32 v66, v67, v66
	v_pk_add_f32 v[8:9], v[6:7], v[10:11] op_sel_hi:[0,1]
	v_cndmask_b32_e32 v1, v28, v29, vcc
	v_cmp_lt_i32_e32 vcc, -1, v9
	v_bitop3_b32 v1, v1, s90, v3 bitop3:0xde
	v_and_b32_e32 v9, 0xffffff00, v9
	v_cndmask_b32_e32 v3, v28, v29, vcc
	v_cmp_lt_i32_e32 vcc, -1, v8
	v_bitop3_b32 v3, v3, 63, v9 bitop3:0xde
	v_and_b32_e32 v8, 0xffffff00, v8
	v_cndmask_b32_e32 v9, v28, v29, vcc
	v_cmp_lt_i32_e32 vcc, -1, v5
	v_and_b32_e32 v5, 0xffffff00, v5
	v_bitop3_b32 v8, v9, 47, v8 bitop3:0xde
	v_cndmask_b32_e32 v6, v28, v29, vcc
	v_cmp_lt_i32_e32 vcc, -1, v4
	v_bitop3_b32 v5, v6, 31, v5 bitop3:0xde
	v_and_b32_e32 v4, 0xffffff00, v4
	v_cndmask_b32_e32 v6, v28, v29, vcc
	v_bitop3_b32 v4, v6, 15, v4 bitop3:0xde
	v_max_u32_e32 v6, v69, v70
	v_min_u32_e32 v9, v69, v70
	v_max_u32_e32 v10, v71, v72
	v_min_u32_e32 v11, v71, v72
	v_max_u32_e32 v67, v64, v73
	v_min_u32_e32 v64, v64, v73
	v_max_u32_e32 v69, v74, v75
	v_min_u32_e32 v70, v74, v75
	v_max_u32_e32 v71, v76, v77
	v_min_u32_e32 v72, v76, v77
	v_max_u32_e32 v73, v22, v78
	v_min_u32_e32 v22, v22, v78
	v_max_u32_e32 v74, v25, v24
	v_min_u32_e32 v24, v25, v24
	v_max_u32_e32 v25, v6, v10
	v_min_u32_e32 v6, v6, v10
	v_max_u32_e32 v10, v9, v11
	v_min_u32_e32 v9, v9, v11
	v_max_u32_e32 v11, v33, v67
	v_min_u32_e32 v33, v33, v67
	v_max_u32_e32 v67, v66, v64
	v_min_u32_e32 v64, v66, v64
	v_max_u32_e32 v66, v69, v71
	v_min_u32_e32 v69, v69, v71
	v_max_u32_e32 v71, v70, v72
	v_min_u32_e32 v70, v70, v72
	v_max_u32_e32 v72, v73, v74
	v_min_u32_e32 v73, v73, v74
	v_max_u32_e32 v74, v22, v24
	v_min_u32_e32 v22, v22, v24
	v_max_u32_e32 v24, v10, v6
	v_min_u32_e32 v6, v10, v6
	v_max_u32_e32 v10, v67, v33
	v_min_u32_e32 v33, v67, v33
	v_max_u32_e32 v67, v71, v69
	v_min_u32_e32 v69, v71, v69
	v_max_u32_e32 v71, v74, v73
	v_min_u32_e32 v73, v74, v73
	v_max_u32_e32 v74, v25, v11
	v_min_u32_e32 v11, v25, v11
	v_max_u32_e32 v25, v24, v10
	v_min_u32_e32 v10, v24, v10
	v_max_u32_e32 v24, v6, v33
	v_min_u32_e32 v6, v6, v33
	v_max_u32_e32 v33, v9, v64
	v_min_u32_e32 v9, v9, v64
	v_max_u32_e32 v64, v66, v72
	v_min_u32_e32 v66, v66, v72
	v_max_u32_e32 v72, v67, v71
	v_min_u32_e32 v67, v67, v71
	v_max_u32_e32 v71, v69, v73
	v_min_u32_e32 v69, v69, v73
	v_max_u32_e32 v73, v70, v22
	v_min_u32_e32 v22, v70, v22
	v_max_u32_e32 v70, v24, v11
	v_min_u32_e32 v11, v24, v11
	v_max_u32_e32 v24, v33, v10
	v_min_u32_e32 v10, v33, v10
	v_max_u32_e32 v33, v71, v66
	v_min_u32_e32 v66, v71, v66
	v_max_u32_e32 v71, v73, v67
	v_min_u32_e32 v67, v73, v67
	v_max_u32_e32 v73, v25, v70
	v_min_u32_e32 v25, v25, v70
	v_max_u32_e32 v70, v24, v11
	v_min_u32_e32 v11, v24, v11
	v_max_u32_e32 v24, v10, v6
	v_min_u32_e32 v6, v10, v6
	v_max_u32_e32 v10, v72, v33
	v_min_u32_e32 v33, v72, v33
	v_max_u32_e32 v72, v71, v66
	v_min_u32_e32 v66, v71, v66
	v_max_u32_e32 v71, v67, v69
	v_min_u32_e32 v67, v67, v69
	v_max_u32_e32 v79, v16, v80
	v_min_u32_e32 v16, v16, v80
	v_max_u32_e32 v80, v18, v32
	v_min_u32_e32 v18, v18, v32
	v_max_u32_e32 v32, v7, v30
	v_min_u32_e32 v7, v7, v30
	v_max_u32_e32 v30, v31, v1
	v_min_u32_e32 v1, v31, v1
	v_max_u32_e32 v31, v3, v8
	v_min_u32_e32 v3, v3, v8
	v_min_u32_e32 v69, v74, v64
	v_max_u32_e32 v75, v73, v10
	v_min_u32_e32 v10, v73, v10
	v_max_u32_e32 v73, v25, v33
	v_min_u32_e32 v25, v25, v33
	v_max_u32_e32 v33, v70, v72
	v_min_u32_e32 v70, v70, v72
	v_max_u32_e32 v72, v11, v66
	v_min_u32_e32 v11, v11, v66
	v_max_u32_e32 v66, v24, v71
	v_min_u32_e32 v24, v24, v71
	v_max_u32_e32 v71, v6, v67
	v_min_u32_e32 v6, v6, v67
	v_max_u32_e32 v67, v9, v22
	v_max_u32_e32 v8, v84, v13
	v_min_u32_e32 v13, v84, v13
	v_max_u32_e32 v84, v12, v20
	v_min_u32_e32 v12, v12, v20
	v_max_u32_e32 v20, v21, v79
	v_min_u32_e32 v21, v21, v79
	v_max_u32_e32 v79, v14, v16
	v_min_u32_e32 v14, v14, v16
	v_max_u32_e32 v16, v80, v32
	v_min_u32_e32 v32, v80, v32
	v_max_u32_e32 v80, v18, v7
; DI void phase10(const Params& P, char* smem) {
;     ...
;     SORT16(C1) SORT16(C2) SORT16(C3)
;     MERGE16(C0, C1) MERGE16(C0, C2) MERGE16(C0, C3)
	v_min_u32_e32 v7, v18, v7
	v_max_u32_e32 v18, v30, v31
	v_min_u32_e32 v30, v30, v31
	v_max_u32_e32 v31, v1, v3
	v_min_u32_e32 v9, v9, v22
	v_max_u32_e32 v22, v72, v69
	v_min_u32_e32 v69, v72, v69
	v_max_u32_e32 v72, v66, v10
	v_min_u32_e32 v10, v66, v10
	v_max_u32_e32 v66, v71, v25
	v_min_u32_e32 v25, v71, v25
	v_max_u32_e32 v71, v67, v70
	v_min_u32_e32 v67, v67, v70
	v_min_u32_e32 v1, v1, v3
	v_max_u32_e32 v3, v84, v13
	v_min_u32_e32 v13, v84, v13
	v_max_u32_e32 v84, v79, v21
	v_min_u32_e32 v21, v79, v21
	v_max_u32_e32 v79, v80, v32
	v_min_u32_e32 v32, v80, v32
	v_max_u32_e32 v80, v31, v30
	v_min_u32_e32 v30, v31, v30
	v_max_u32_e32 v70, v73, v22
	v_min_u32_e32 v22, v73, v22
	v_max_u32_e32 v73, v33, v72
	v_min_u32_e32 v33, v33, v72
	v_max_u32_e32 v72, v66, v69
	v_min_u32_e32 v66, v66, v69
	v_max_u32_e32 v69, v71, v10
	v_min_u32_e32 v10, v71, v10
	v_max_u32_e32 v71, v25, v11
	v_min_u32_e32 v11, v25, v11
	v_max_u32_e32 v25, v67, v24
	v_min_u32_e32 v24, v67, v24
	v_max_u32_e32 v31, v8, v20
	v_min_u32_e32 v8, v8, v20
	v_max_u32_e32 v20, v3, v84
	v_min_u32_e32 v3, v3, v84
	v_max_u32_e32 v84, v13, v21
	v_min_u32_e32 v13, v13, v21
	v_max_u32_e32 v21, v12, v14
	v_min_u32_e32 v12, v12, v14
	v_max_u32_e32 v14, v16, v18
	v_min_u32_e32 v16, v16, v18
	v_max_u32_e32 v18, v79, v80
	v_min_u32_e32 v79, v79, v80
	v_max_u32_e32 v80, v32, v30
	v_min_u32_e32 v30, v32, v30
	v_max_u32_e32 v32, v7, v1
	v_min_u32_e32 v67, v75, v70
	v_min_u32_e32 v76, v73, v22
	v_min_u32_e32 v77, v33, v72
	v_min_u32_e32 v78, v69, v66
	v_min_u32_e32 v81, v10, v71
	v_min_u32_e32 v82, v25, v11
	v_min_u32_e32 v83, v24, v6
	v_min_u32_e32 v1, v7, v1
	v_max_u32_e32 v7, v84, v8
	v_min_u32_e32 v8, v84, v8
	v_max_u32_e32 v84, v21, v3
	v_min_u32_e32 v3, v21, v3
	v_max_u32_e32 v21, v80, v16
	v_min_u32_e32 v16, v80, v16
	v_max_u32_e32 v80, v32, v79
	v_min_u32_e32 v32, v32, v79
	v_max_u32_e32 v79, v20, v7
	v_min_u32_e32 v7, v20, v7
	v_max_u32_e32 v20, v84, v8
	v_min_u32_e32 v8, v84, v8
	v_max_u32_e32 v84, v3, v13
	v_min_u32_e32 v3, v3, v13
	v_max_u32_e32 v13, v18, v21
	v_min_u32_e32 v18, v18, v21
	v_max_u32_e32 v21, v80, v16
	v_min_u32_e32 v16, v80, v16
	v_max_u32_e32 v80, v32, v30
	v_min_u32_e32 v30, v32, v30
	v_max_u32_e32 v9, v35, v9
	v_max_u32_e32 v35, v36, v83
	v_max3_u32 v6, v37, v24, v6
	v_max_u32_e32 v24, v38, v82
	v_max3_u32 v11, v39, v25, v11
	v_max_u32_e32 v25, v40, v81
	v_max3_u32 v10, v41, v10, v71
	v_max_u32_e32 v36, v57, v78
	v_max3_u32 v37, v58, v69, v66
	v_max_u32_e32 v38, v59, v77
	v_max3_u32 v33, v60, v33, v72
	v_max_u32_e32 v39, v61, v76
	v_max3_u32 v22, v62, v73, v22
	v_max_u32_e32 v40, v63, v67
	v_max3_u32 v41, v65, v75, v70
	v_max3_u32 v57, v68, v74, v64
	v_min_u32_e32 v32, v31, v14
	v_max_u32_e32 v85, v79, v13
	v_min_u32_e32 v13, v79, v13
	v_max_u32_e32 v79, v7, v18
	v_min_u32_e32 v7, v7, v18
	v_max_u32_e32 v18, v20, v21
	v_min_u32_e32 v20, v20, v21
	v_max_u32_e32 v21, v8, v16
	v_min_u32_e32 v8, v8, v16
	v_max_u32_e32 v16, v84, v80
	v_min_u32_e32 v80, v84, v80
	v_max_u32_e32 v84, v3, v30
	v_min_u32_e32 v3, v3, v30
	v_max_u32_e32 v30, v12, v1
	v_max_u32_e32 v58, v9, v37
	v_min_u32_e32 v9, v9, v37
	v_max_u32_e32 v37, v35, v38
	v_min_u32_e32 v35, v35, v38
	v_max_u32_e32 v38, v6, v33
	v_min_u32_e32 v6, v6, v33
	v_max_u32_e32 v33, v24, v39
	v_min_u32_e32 v24, v24, v39
	v_max_u32_e32 v39, v11, v22
	v_min_u32_e32 v11, v11, v22
	v_max_u32_e32 v22, v25, v40
	v_min_u32_e32 v25, v25, v40
	v_max_u32_e32 v40, v10, v41
	v_min_u32_e32 v10, v10, v41
	v_max_u32_e32 v41, v36, v57
	v_min_u32_e32 v36, v36, v57
	v_min_u32_e32 v1, v12, v1
	v_max_u32_e32 v12, v21, v32
	v_min_u32_e32 v21, v21, v32
	v_max_u32_e32 v32, v16, v13
	v_min_u32_e32 v13, v16, v13
	v_max_u32_e32 v16, v84, v7
	v_min_u32_e32 v7, v84, v7
	v_max_u32_e32 v84, v30, v20
	v_min_u32_e32 v20, v30, v20
	v_max_u32_e32 v57, v58, v39
	v_min_u32_e32 v39, v58, v39
	v_max_u32_e32 v58, v37, v22
	v_min_u32_e32 v22, v37, v22
	v_max_u32_e32 v37, v38, v40
	v_min_u32_e32 v38, v38, v40
	v_max_u32_e32 v40, v33, v41
	v_min_u32_e32 v33, v33, v41
	v_max_u32_e32 v41, v9, v11
	v_min_u32_e32 v9, v9, v11
	v_max_u32_e32 v11, v35, v25
	v_min_u32_e32 v25, v35, v25
	v_max_u32_e32 v35, v6, v10
	v_min_u32_e32 v6, v6, v10
	v_max_u32_e32 v10, v24, v36
	v_min_u32_e32 v24, v24, v36
	v_max_u32_e32 v30, v79, v12
	v_min_u32_e32 v12, v79, v12
	v_max_u32_e32 v79, v18, v32
	v_min_u32_e32 v18, v18, v32
	v_max_u32_e32 v32, v16, v21
	v_min_u32_e32 v16, v16, v21
	v_max_u32_e32 v21, v84, v13
; DI unsigned lut4(const unsigned (&W)[4], int a) { const int j = a >> 2; const unsigned w = j == 0 ? W[0] : (j == 1 ? W[1] : (j == 2 ? W[2] : W[3])); return (w >> ((a & 3) * 8)) & 0xffu; }
; DI void phase10(const Params& P, char* smem) {
;     ...
;     MERGE16(C0, C1) MERGE16(C0, C2) MERGE16(C0, C3)
;     float e[16]; int te[16]; float sum = 0.f;
;     const float tv0 = [&]() { const unsigned o = C0[0] & 0xffffff00u; return __uint_as_float((o >> 31) ? (o ^ 0x80000000u) : ~o); }();
; #pragma unroll
;     for (int k = 0; k < 16; ++k) {
;       const unsigned key = C0[k]; const unsigned o = key & 0xffffff00u;
;       const float val = __uint_as_float((o >> 31) ? (o ^ 0x80000000u) : ~o);
;       const int pos = 255 - (int)(key & 255u);
;       te[k] = (int)(lut4(W1, pos >> 4) * 128u + lut4(W2, pos & 15));
	v_min_u32_e32 v13, v84, v13
	v_max_u32_e32 v84, v7, v8
	v_min_u32_e32 v7, v7, v8
	v_max_u32_e32 v8, v20, v80
	v_min_u32_e32 v20, v20, v80
	v_max_u32_e32 v36, v57, v37
	v_min_u32_e32 v37, v57, v37
	v_max_u32_e32 v57, v58, v40
	v_min_u32_e32 v40, v58, v40
	v_max_u32_e32 v58, v39, v38
	v_min_u32_e32 v38, v39, v38
	v_max_u32_e32 v39, v22, v33
	v_min_u32_e32 v22, v22, v33
	v_max_u32_e32 v33, v41, v35
	v_min_u32_e32 v35, v41, v35
	v_max_u32_e32 v41, v11, v10
	v_min_u32_e32 v10, v11, v10
	v_max_u32_e32 v11, v9, v6
	v_min_u32_e32 v6, v9, v6
	v_max_u32_e32 v9, v25, v24
	v_min_u32_e32 v24, v25, v24
	v_max_u32_e32 v80, v85, v30
	v_min_u32_e32 v30, v85, v30
	v_max_u32_e32 v85, v79, v12
	v_min_u32_e32 v12, v79, v12
	v_max_u32_e32 v79, v18, v32
	v_min_u32_e32 v18, v18, v32
	v_max_u32_e32 v32, v21, v16
	v_min_u32_e32 v16, v21, v16
	v_max_u32_e32 v21, v13, v84
	v_min_u32_e32 v13, v13, v84
	v_max_u32_e32 v84, v8, v7
	v_min_u32_e32 v7, v8, v7
	v_max_u32_e32 v8, v20, v3
	v_min_u32_e32 v3, v20, v3
	v_min_u32_e32 v25, v36, v57
	v_min_u32_e32 v59, v37, v40
	v_min_u32_e32 v60, v58, v39
	v_min_u32_e32 v61, v38, v22
	v_min_u32_e32 v62, v33, v41
	v_min_u32_e32 v63, v35, v10
	v_min_u32_e32 v64, v11, v9
	v_min_u32_e32 v65, v6, v24
	v_max3_u32 v1, v36, v57, v1
	v_max_u32_e32 v3, v25, v3
	v_max3_u32 v8, v37, v40, v8
	v_max_u32_e32 v7, v59, v7
	v_max3_u32 v25, v58, v39, v84
	v_max_u32_e32 v13, v60, v13
	v_max3_u32 v21, v38, v22, v21
	v_max_u32_e32 v16, v61, v16
	v_max3_u32 v22, v33, v41, v32
	v_max_u32_e32 v18, v62, v18
	v_max3_u32 v10, v35, v10, v79
	v_max_u32_e32 v12, v63, v12
	v_max3_u32 v9, v11, v9, v85
	v_max_u32_e32 v11, v64, v30
	v_max3_u32 v6, v6, v24, v80
	v_max3_u32 v14, v65, v31, v14
	v_max_u32_e32 v24, v1, v22
	v_min_u32_e32 v1, v1, v22
	v_max_u32_e32 v22, v3, v18
	v_min_u32_e32 v3, v3, v18
	v_max_u32_e32 v18, v8, v10
	v_min_u32_e32 v8, v8, v10
	v_max_u32_e32 v10, v7, v12
	v_min_u32_e32 v7, v7, v12
	v_max_u32_e32 v12, v25, v9
	v_min_u32_e32 v9, v25, v9
	v_max_u32_e32 v25, v13, v11
	v_min_u32_e32 v11, v13, v11
	v_max_u32_e32 v13, v21, v6
	v_min_u32_e32 v6, v21, v6
	v_max_u32_e32 v21, v16, v14
	v_min_u32_e32 v14, v16, v14
	v_max_u32_e32 v16, v24, v12
	v_min_u32_e32 v12, v24, v12
	v_max_u32_e32 v24, v22, v25
	v_min_u32_e32 v22, v22, v25
	v_max_u32_e32 v25, v18, v13
	v_min_u32_e32 v13, v18, v13
	v_max_u32_e32 v18, v10, v21
	v_min_u32_e32 v10, v10, v21
	v_max_u32_e32 v21, v1, v9
	v_min_u32_e32 v1, v1, v9
	v_max_u32_e32 v9, v3, v11
	v_min_u32_e32 v3, v3, v11
	v_max_u32_e32 v11, v8, v6
	v_min_u32_e32 v6, v8, v6
	v_max_u32_e32 v8, v7, v14
	v_min_u32_e32 v7, v7, v14
	v_max_u32_e32 v14, v16, v25
	v_min_u32_e32 v16, v16, v25
	v_max_u32_e32 v25, v24, v18
	v_min_u32_e32 v18, v24, v18
	v_max_u32_e32 v24, v12, v13
	v_min_u32_e32 v12, v12, v13
	v_max_u32_e32 v13, v22, v10
	v_min_u32_e32 v10, v22, v10
	v_max_u32_e32 v22, v21, v11
	v_min_u32_e32 v11, v21, v11
	v_max_u32_e32 v21, v9, v8
	v_min_u32_e32 v8, v9, v8
	v_max_u32_e32 v9, v1, v6
	v_min_u32_e32 v1, v1, v6
	v_max_u32_e32 v6, v3, v7
	v_min_u32_e32 v3, v3, v7
	v_min_u32_e32 v20, v5, v4
	v_max_u32_e32 v69, v9, v6
	v_min_u32_e32 v70, v9, v6
	v_min_u32_e32 v6, v1, v3
	v_max_u32_e32 v57, v14, v25
	v_min_u32_e32 v58, v14, v25
	v_max_u32_e32 v59, v16, v18
	v_min_u32_e32 v60, v16, v18
	v_max_u32_e32 v61, v24, v13
	v_min_u32_e32 v62, v24, v13
	v_max_u32_e32 v63, v12, v10
	v_min_u32_e32 v64, v12, v10
	v_max_u32_e32 v65, v22, v21
	v_min_u32_e32 v66, v22, v21
	v_max_u32_e32 v67, v11, v8
	v_min_u32_e32 v68, v11, v8
	v_max3_u32 v71, v1, v3, v20
	v_max3_u32 v72, v6, v5, v4
	v_max_u32_e32 v11, v57, v65
	v_max_u32_e32 v12, v58, v66
	v_max_u32_e32 v13, v59, v67
	v_max_u32_e32 v32, v60, v68
	v_max_u32_e32 v33, v61, v69
	v_max_u32_e32 v35, v62, v70
	v_max_u32_e32 v36, v63, v71
	v_max_u32_e32 v37, v64, v72
	v_max_u32_e32 v9, v11, v33
	v_max_u32_e32 v10, v12, v35
	v_max_u32_e32 v22, v13, v36
	v_max_u32_e32 v24, v32, v37
	v_max_u32_e32 v8, v9, v22
	v_max_u32_e32 v18, v10, v24
	v_max_u32_e32 v4, v8, v18
	v_bitop3_b32 v1, v4, s3, v4 bitop3:0xc
	v_cmp_lt_u32_e32 vcc, 63, v1
	v_mov_b32_e32 v3, v15
	s_and_saveexec_b64 s[0:1], vcc
	s_cbranch_execz .LBB0_1193
	v_lshrrev_b32_e32 v5, 6, v1
	v_cmp_lt_i32_e32 vcc, 1, v5
	s_mov_b64 s[6:7], 0
	s_and_saveexec_b64 s[8:9], vcc
	s_xor_b64 s[8:9], exec, s[8:9]
	s_cbranch_execnz .LBB0_1381
	s_or_saveexec_b64 s[8:9], s[8:9]
	v_mov_b32_e32 v3, v19
	s_xor_b64 exec, exec, s[8:9]
	s_cbranch_execnz .LBB0_1384
